# YA8 layout [b][group/4][token][group%4][16]: P4 A-operand LDS-DMA lanes quad-contiguous (64 B), P3 stores remapped
# speedup vs baseline: 1.0086x; 1.0086x over previous
; #define LAS __attribute__((address_space(3)))
; __global__ void __launch_bounds__(NWAVES * 64, 2) trunk_fwd(Args a) {
;     extern __shared__ __attribute__((aligned(16))) unsigned char lds_raw[];
;     Ctx F; F.lds = (LAS unsigned char*)lds_raw; F.tid = threadIdx.x; F.lane = F.tid & 63; F.wave = __builtin_amdgcn_readfirstlane(F.tid >> 6);
;     F.G = gridDim.x; F.wg = blockIdx.x;
;     volatile LAS unsigned* MISC = (volatile LAS unsigned*)(F.lds + MISC_OFF);
;     if (F.tid < 64) MISC[F.tid] = 0u;
;     __syncthreads();
;     unsigned* ctl = (unsigned*)(a.ws + WS_CTL);
;     XcdBarrier bar; bar.bar = ctl + CW_BAR; bar.x = 0; bar.st = nullptr;
_Z9trunk_fwd4Args:
	s_mov_b32 s98, 0x7ffc0
	s_load_dwordx16 s[16:31], s[0:1], 0x80
	s_load_dwordx2 s[14:15], s[0:1], 0xc0
	s_load_dword s3, s[0:1], 0xc8
	v_readfirstlane_b32 s4, v0
	v_cmp_gt_u32_e32 vcc, 64, v0
	s_nop 0
	v_writelane_b32 v252, s4, 0
	s_add_u32 s4, s0, 0xc8
	s_addc_u32 s5, s1, 0
	v_writelane_b32 v252, s4, 1
	s_nop 1
	v_writelane_b32 v252, s5, 2
	s_and_saveexec_b64 s[4:5], vcc
	v_lshl_add_u32 v1, v0, 2, 0
	v_add_u32_e32 v1, 0x20000, v1
	v_mov_b32_e32 v2, 0
	ds_write_b32 v1, v2
	s_or_b64 exec, exec, s[4:5]
	s_load_dwordx16 s[36:51], s[0:1], 0x0
	s_waitcnt lgkmcnt(0)
	s_add_u32 s96, s30, 0x4000
	s_barrier
	s_addc_u32 s97, s31, 0
	s_getreg_b32 s6, hwreg(HW_REG_XCC_ID, 0, 4)
	v_cmp_eq_u32_e64 s[8:9], 0, v0
	s_mov_b64 s[4:5], exec
	s_nop 0
	v_writelane_b32 v252, s8, 3
	s_nop 1
	v_writelane_b32 v252, s9, 4
	s_and_b64 s[8:9], s[4:5], s[8:9]
	s_mov_b64 exec, s[8:9]
	s_cbranch_execz .LBB0_5
	s_mov_b64 s[8:9], exec
	v_mbcnt_lo_u32_b32 v0, s8, 0
	v_mbcnt_hi_u32_b32 v0, s9, v0
	v_cmp_eq_u32_e32 vcc, 0, v0
	s_and_b64 s[10:11], exec, vcc
	s_mov_b64 exec, s[10:11]
	s_cbranch_execz .LBB0_5
	s_lshl_b32 s6, s6, 8
	s_and_b32 s6, s6, 0xf00
	s_bcnt1_i32_b64 s7, s[8:9]
	v_mov_b32_e32 v0, s6
	v_mov_b32_e32 v1, s7
	global_atomic_add v0, v1, s[96:97] offset:1024

; __device__ __forceinline__ unsigned cvt_pk_bf16(float lo, float hi) { unsigned r; asm volatile("v_cvt_pk_bf16_f32 %0, %1, %2" : "=v"(r) : "v"(lo), "v"(hi)); return r; }
; __device__ __forceinline__ float bf_lo(unsigned w) { return __uint_as_float(w << 16); }
; __device__ __forceinline__ float bf_hi(unsigned w) { return __uint_as_float(w & 0xffff0000u); }
; template <bool REV> ...
;     ...
;                 else { const u32x2 p = pv[th][sx], u = uv[th][sx];
;                     const f32x2 v01 = (f32x2){y[0], y[1]} + (f32x2){bf_lo(p.x), bf_hi(p.x)} + dsk01 * (f32x2){bf_lo(u.x), bf_hi(u.x)};
;                     const f32x2 v23 = (f32x2){y[2], y[3]} + (f32x2){bf_lo(p.y), bf_hi(p.y)} + dsk23 * (f32x2){bf_lo(u.y), bf_hi(u.y)};
;                     const f32x2 o01 = gelu2(v01), o23 = gelu2(v23);
;                     u32x2 w; w.x = cvt_pk_bf16(o01.x, o01.y); w.y = cvt_pk_bf16(o23.x, o23.y); *(u32x2*)yo = w;
;                     { const unsigned x8 = pack_i8x4(o01.x, o01.y, o23.x, o23.y, 1.0f / YA8_R);
;                       *(unsigned*)(Y8 + (yo - YA)) = x8; }
;                     pv[th][sx] = *(const u32x2*)(yo + adv); uv[th][sx] = *(const u32x2*)(pU + th * CSTEP16 + sx * SSTEP + adv); }
.LBB0_385:
	s_andn2_b64 vcc, exec, s[0:1]
	s_cbranch_vccnz .LBB0_387
	v_lshlrev_b32_e32 v24, 16, v192
	v_and_b32_e32 v25, 0xffff0000, v192
	s_nop 2
	v_pk_add_f32 v[20:21], v[20:21], v[24:25]
	v_lshlrev_b32_e32 v24, 16, v190
	v_and_b32_e32 v25, 0xffff0000, v190
	v_pk_fma_f32 v[20:21], v[64:65], v[24:25], v[20:21]
	v_lshlrev_b32_e32 v24, 16, v193
	v_and_b32_e32 v25, 0xffff0000, v193
	v_pk_add_f32 v[22:23], v[22:23], v[24:25]
	v_lshlrev_b32_e32 v24, 16, v191
	v_and_b32_e32 v25, 0xffff0000, v191
	v_pk_fma_f32 v[22:23], v[66:67], v[24:25], v[22:23]
	v_pk_mul_f32 v[24:25], v[20:21], v[20:21]
	v_mov_b64_e32 v[26:27], s[22:23]
	v_pk_fma_f32 v[24:25], v[24:25], s[18:19], v[26:27] op_sel_hi:[1,0,0] neg_lo:[1,0,0] neg_hi:[1,0,0]
	v_pk_mul_f32 v[28:29], v[22:23], v[22:23]
	v_pk_mul_f32 v[24:25], v[20:21], v[24:25]
	v_pk_fma_f32 v[26:27], v[28:29], s[18:19], v[26:27] op_sel_hi:[1,0,0] neg_lo:[1,0,0] neg_hi:[1,0,0]
	v_exp_f32_e32 v24, v24
	v_exp_f32_e32 v25, v25
	v_pk_mul_f32 v[26:27], v[22:23], v[26:27]
	v_pk_add_f32 v[24:25], v[24:25], 1.0 op_sel_hi:[1,0]
	v_exp_f32_e32 v26, v26
	v_exp_f32_e32 v27, v27
	v_rcp_f32_e32 v24, v24
	v_rcp_f32_e32 v25, v25
	v_pk_add_f32 v[26:27], v[26:27], 1.0 op_sel_hi:[1,0]
	s_nop 0
	v_rcp_f32_e32 v26, v26
	v_rcp_f32_e32 v27, v27
	v_pk_mul_f32 v[20:21], v[20:21], v[24:25]
	v_pk_mul_f32 v[22:23], v[22:23], v[26:27]
	v_cvt_pk_bf16_f32 v24, v20, v21
	v_mul_f32_e32 v14, 0x3d924925, v20
	v_mul_f32_e32 v20, 0x3d924925, v21
	v_cvt_pknorm_i16_f32 v14, v14, v20
	v_mul_f32_e32 v20, 0x3d924925, v22
	v_mul_f32_e32 v21, 0x3d924925, v23
	v_cvt_pknorm_i16_f32 v20, v20, v21
	v_pk_add_i16 v14, v14, s54 op_sel_hi:[1,0] clamp
	v_pk_add_i16 v20, v20, s54 op_sel_hi:[1,0] clamp
	v_mov_b32_e32 v21, s7
	v_perm_b32 v14, v20, v14, s55
	v_subrev_co_u32_e32 v20, vcc, s6, v200
	v_cvt_pk_bf16_f32 v25, v22, v23
	global_store_dwordx2 v[200:201], v[24:25], off
	s_nop 0
	v_subb_co_u32_e32 v21, vcc, v201, v21, vcc
	v_ashrrev_i64 v[20:21], 1, v[20:21]
	v_bfe_u32 v21, v20, 4, 15
	v_lshlrev_b32_e32 v21, 6, v21
	v_bfi_b32 v20, s98, v21, v20
	v_lshrrev_b32_e32 v21, 15, v21
	v_bfi_b32 v20, 48, v21, v20
	global_store_dword v20, v14, s[8:9]
	v_add_co_u32_e32 v20, vcc, 0x4c3ff000, v198
	s_nop 1
	v_addc_co_u32_e32 v21, vcc, 0, v199, vcc
	v_add_co_u32_e32 v22, vcc, 0x2bbff000, v198
	s_nop 1
	v_addc_co_u32_e32 v23, vcc, 0, v199, vcc
	global_load_dwordx2 v[192:193], v[20:21], off offset:2048
	global_load_dwordx2 v[190:191], v[22:23], off offset:2048

; __device__ __forceinline__ unsigned cvt_pk_bf16(float lo, float hi) { unsigned r; asm volatile("v_cvt_pk_bf16_f32 %0, %1, %2" : "=v"(r) : "v"(lo), "v"(hi)); return r; }
; __device__ __forceinline__ float bf_lo(unsigned w) { return __uint_as_float(w << 16); }
; __device__ __forceinline__ float bf_hi(unsigned w) { return __uint_as_float(w & 0xffff0000u); }
; template <bool REV> ...
;     ...
;                 else { const u32x2 p = pv[th][sx], u = uv[th][sx];
;                     const f32x2 v01 = (f32x2){y[0], y[1]} + (f32x2){bf_lo(p.x), bf_hi(p.x)} + dsk01 * (f32x2){bf_lo(u.x), bf_hi(u.x)};
;                     const f32x2 v23 = (f32x2){y[2], y[3]} + (f32x2){bf_lo(p.y), bf_hi(p.y)} + dsk23 * (f32x2){bf_lo(u.y), bf_hi(u.y)};
;                     const f32x2 o01 = gelu2(v01), o23 = gelu2(v23);
;                     u32x2 w; w.x = cvt_pk_bf16(o01.x, o01.y); w.y = cvt_pk_bf16(o23.x, o23.y); *(u32x2*)yo = w;
;                     { const unsigned x8 = pack_i8x4(o01.x, o01.y, o23.x, o23.y, 1.0f / YA8_R);
;                       *(unsigned*)(Y8 + (yo - YA)) = x8; }
;                     pv[th][sx] = *(const u32x2*)(yo + adv); uv[th][sx] = *(const u32x2*)(pU + th * CSTEP16 + sx * SSTEP + adv); }
.LBB0_389:
	s_andn2_b64 vcc, exec, s[50:51]
	s_cbranch_vccnz .LBB0_391
	v_lshlrev_b32_e32 v4, 16, v188
	v_and_b32_e32 v5, 0xffff0000, v188
	s_nop 2
	v_pk_add_f32 v[0:1], v[0:1], v[4:5]
	v_lshlrev_b32_e32 v4, 16, v186
	v_and_b32_e32 v5, 0xffff0000, v186
	v_pk_fma_f32 v[0:1], v[64:65], v[4:5], v[0:1]
	v_lshlrev_b32_e32 v4, 16, v189
	v_and_b32_e32 v5, 0xffff0000, v189
	v_pk_add_f32 v[2:3], v[2:3], v[4:5]
	v_lshlrev_b32_e32 v4, 16, v187
	v_and_b32_e32 v5, 0xffff0000, v187
	v_pk_fma_f32 v[2:3], v[66:67], v[4:5], v[2:3]
	v_pk_mul_f32 v[4:5], v[0:1], v[0:1]
	v_mov_b64_e32 v[6:7], s[22:23]
	v_pk_fma_f32 v[4:5], v[4:5], s[18:19], v[6:7] op_sel_hi:[1,0,0] neg_lo:[1,0,0] neg_hi:[1,0,0]
	v_pk_mul_f32 v[10:11], v[2:3], v[2:3]
	v_pk_mul_f32 v[4:5], v[0:1], v[4:5]
	v_pk_fma_f32 v[6:7], v[10:11], s[18:19], v[6:7] op_sel_hi:[1,0,0] neg_lo:[1,0,0] neg_hi:[1,0,0]
	v_exp_f32_e32 v4, v4
	v_exp_f32_e32 v5, v5
	v_pk_mul_f32 v[6:7], v[2:3], v[6:7]
	v_pk_add_f32 v[4:5], v[4:5], 1.0 op_sel_hi:[1,0]
	v_exp_f32_e32 v6, v6
	v_exp_f32_e32 v7, v7
	v_rcp_f32_e32 v4, v4
	v_rcp_f32_e32 v5, v5
	v_pk_add_f32 v[6:7], v[6:7], 1.0 op_sel_hi:[1,0]
	s_nop 0
	v_rcp_f32_e32 v6, v6
	v_rcp_f32_e32 v7, v7
	v_pk_mul_f32 v[0:1], v[0:1], v[4:5]
	v_pk_mul_f32 v[2:3], v[2:3], v[6:7]
	v_cvt_pk_bf16_f32 v4, v0, v1
	v_mul_f32_e32 v0, 0x3d924925, v0
	v_mul_f32_e32 v1, 0x3d924925, v1
	v_cvt_pk_bf16_f32 v5, v2, v3
	v_cvt_pknorm_i16_f32 v0, v0, v1
	v_mul_f32_e32 v1, 0x3d924925, v2
	v_mul_f32_e32 v2, 0x3d924925, v3
	v_cvt_pknorm_i16_f32 v1, v1, v2
	v_pk_add_i16 v0, v0, s54 op_sel_hi:[1,0] clamp
	v_pk_add_i16 v1, v1, s54 op_sel_hi:[1,0] clamp
	global_store_dwordx2 v[8:9], v[4:5], off
	v_perm_b32 v2, v1, v0, s55
	v_mov_b32_e32 v1, s7
	v_subrev_co_u32_e32 v0, vcc, s6, v8
	s_nop 1
	v_subb_co_u32_e32 v1, vcc, v9, v1, vcc
	v_ashrrev_i64 v[0:1], 1, v[0:1]
	v_bfe_u32 v1, v0, 4, 15
	v_lshlrev_b32_e32 v1, 6, v1
	v_bfi_b32 v0, s98, v1, v0
	v_lshrrev_b32_e32 v1, 15, v1
	v_bfi_b32 v0, 48, v1, v0
	global_store_dword v0, v2, s[8:9]
	v_add_co_u32_e32 v0, vcc, 0x4c3ff000, v198
	s_nop 1
	v_addc_co_u32_e32 v1, vcc, 0, v199, vcc
	v_add_co_u32_e32 v2, vcc, 0x2bbff000, v198
	s_nop 1
	v_addc_co_u32_e32 v3, vcc, 0, v199, vcc
	global_load_dwordx2 v[188:189], v[0:1], off offset:2016
	global_load_dwordx2 v[186:187], v[2:3], off offset:2016

; __device__ __forceinline__ unsigned cvt_pk_bf16(float lo, float hi) { unsigned r; asm volatile("v_cvt_pk_bf16_f32 %0, %1, %2" : "=v"(r) : "v"(lo), "v"(hi)); return r; }
; __device__ __forceinline__ float bf_lo(unsigned w) { return __uint_as_float(w << 16); }
; __device__ __forceinline__ float bf_hi(unsigned w) { return __uint_as_float(w & 0xffff0000u); }
; template <bool REV> ...
;     ...
;                 else { const u32x2 p = pv[th][sx], u = uv[th][sx];
;                     const f32x2 v01 = (f32x2){y[0], y[1]} + (f32x2){bf_lo(p.x), bf_hi(p.x)} + dsk01 * (f32x2){bf_lo(u.x), bf_hi(u.x)};
;                     const f32x2 v23 = (f32x2){y[2], y[3]} + (f32x2){bf_lo(p.y), bf_hi(p.y)} + dsk23 * (f32x2){bf_lo(u.y), bf_hi(u.y)};
;                     const f32x2 o01 = gelu2(v01), o23 = gelu2(v23);
;                     u32x2 w; w.x = cvt_pk_bf16(o01.x, o01.y); w.y = cvt_pk_bf16(o23.x, o23.y); *(u32x2*)yo = w;
;                     { const unsigned x8 = pack_i8x4(o01.x, o01.y, o23.x, o23.y, 1.0f / YA8_R);
;                       *(unsigned*)(Y8 + (yo - YA)) = x8; }
;                     pv[th][sx] = *(const u32x2*)(yo + adv); uv[th][sx] = *(const u32x2*)(pU + th * CSTEP16 + sx * SSTEP + adv); }
.LBB0_393:
	s_andn2_b64 vcc, exec, s[46:47]
	s_cbranch_vccnz .LBB0_395
	v_lshlrev_b32_e32 v28, 16, v180
	v_and_b32_e32 v29, 0xffff0000, v180
	s_nop 2
	v_pk_add_f32 v[20:21], v[20:21], v[28:29]
	v_lshlrev_b32_e32 v28, 16, v182
	v_and_b32_e32 v29, 0xffff0000, v182
	v_pk_fma_f32 v[20:21], v[64:65], v[28:29], v[20:21]
	v_lshlrev_b32_e32 v28, 16, v181
	v_and_b32_e32 v29, 0xffff0000, v181
	v_pk_add_f32 v[22:23], v[22:23], v[28:29]
	v_lshlrev_b32_e32 v28, 16, v183
	v_and_b32_e32 v29, 0xffff0000, v183
	v_pk_fma_f32 v[22:23], v[66:67], v[28:29], v[22:23]
	v_pk_mul_f32 v[28:29], v[20:21], v[20:21]
	v_mov_b64_e32 v[32:33], s[22:23]
	v_pk_fma_f32 v[28:29], v[28:29], s[18:19], v[32:33] op_sel_hi:[1,0,0] neg_lo:[1,0,0] neg_hi:[1,0,0]
	v_pk_mul_f32 v[34:35], v[22:23], v[22:23]
	v_pk_mul_f32 v[28:29], v[20:21], v[28:29]
	v_pk_fma_f32 v[32:33], v[34:35], s[18:19], v[32:33] op_sel_hi:[1,0,0] neg_lo:[1,0,0] neg_hi:[1,0,0]
	v_exp_f32_e32 v28, v28
	v_exp_f32_e32 v29, v29
	v_pk_mul_f32 v[32:33], v[22:23], v[32:33]
	v_pk_add_f32 v[28:29], v[28:29], 1.0 op_sel_hi:[1,0]
	v_exp_f32_e32 v32, v32
	v_exp_f32_e32 v33, v33
	v_rcp_f32_e32 v28, v28
	v_rcp_f32_e32 v29, v29
	v_pk_add_f32 v[32:33], v[32:33], 1.0 op_sel_hi:[1,0]
	s_nop 0
	v_rcp_f32_e32 v32, v32
	v_rcp_f32_e32 v33, v33
	v_pk_mul_f32 v[20:21], v[20:21], v[28:29]
	v_pk_mul_f32 v[22:23], v[22:23], v[32:33]
	v_cvt_pk_bf16_f32 v28, v20, v21
	v_mul_f32_e32 v14, 0x3d924925, v20
	v_mul_f32_e32 v20, 0x3d924925, v21
	v_cvt_pknorm_i16_f32 v14, v14, v20
	v_mul_f32_e32 v20, 0x3d924925, v22
	v_mul_f32_e32 v21, 0x3d924925, v23
	v_cvt_pknorm_i16_f32 v20, v20, v21
	v_pk_add_i16 v14, v14, s54 op_sel_hi:[1,0] clamp
	v_pk_add_i16 v20, v20, s54 op_sel_hi:[1,0] clamp
	v_mov_b32_e32 v21, s7
	v_perm_b32 v14, v20, v14, s55
	v_subrev_co_u32_e32 v20, vcc, s6, v26
	v_cvt_pk_bf16_f32 v29, v22, v23
	global_store_dwordx2 v[26:27], v[28:29], off
	s_nop 0
	v_subb_co_u32_e32 v21, vcc, v27, v21, vcc
	v_ashrrev_i64 v[20:21], 1, v[20:21]
	v_bfe_u32 v21, v20, 4, 15
	v_lshlrev_b32_e32 v21, 6, v21
	v_bfi_b32 v20, s98, v21, v20
	v_lshrrev_b32_e32 v21, 15, v21
	v_bfi_b32 v20, 48, v21, v20
	global_store_dword v20, v14, s[8:9]
	v_add_co_u32_e32 v20, vcc, 0x4c3ff000, v198
	s_nop 1
	v_addc_co_u32_e32 v21, vcc, 0, v199, vcc
	v_add_co_u32_e32 v22, vcc, 0x2bbff000, v198
	s_nop 1
	v_addc_co_u32_e32 v23, vcc, 0, v199, vcc
	global_load_dwordx2 v[180:181], v[20:21], off offset:1024
	global_load_dwordx2 v[182:183], v[22:23], off offset:1024

; __device__ __forceinline__ unsigned cvt_pk_bf16(float lo, float hi) { unsigned r; asm volatile("v_cvt_pk_bf16_f32 %0, %1, %2" : "=v"(r) : "v"(lo), "v"(hi)); return r; }
; __device__ __forceinline__ float bf_lo(unsigned w) { return __uint_as_float(w << 16); }
; __device__ __forceinline__ float bf_hi(unsigned w) { return __uint_as_float(w & 0xffff0000u); }
; template <bool REV> ...
;     ...
;                 else { const u32x2 p = pv[th][sx], u = uv[th][sx];
;                     const f32x2 v01 = (f32x2){y[0], y[1]} + (f32x2){bf_lo(p.x), bf_hi(p.x)} + dsk01 * (f32x2){bf_lo(u.x), bf_hi(u.x)};
;                     const f32x2 v23 = (f32x2){y[2], y[3]} + (f32x2){bf_lo(p.y), bf_hi(p.y)} + dsk23 * (f32x2){bf_lo(u.y), bf_hi(u.y)};
;                     const f32x2 o01 = gelu2(v01), o23 = gelu2(v23);
;                     u32x2 w; w.x = cvt_pk_bf16(o01.x, o01.y); w.y = cvt_pk_bf16(o23.x, o23.y); *(u32x2*)yo = w;
;                     { const unsigned x8 = pack_i8x4(o01.x, o01.y, o23.x, o23.y, 1.0f / YA8_R);
;                       *(unsigned*)(Y8 + (yo - YA)) = x8; }
;                     pv[th][sx] = *(const u32x2*)(yo + adv); uv[th][sx] = *(const u32x2*)(pU + th * CSTEP16 + sx * SSTEP + adv); }
.LBB0_397:
	s_andn2_b64 vcc, exec, s[46:47]
	s_cbranch_vccnz .LBB0_380
	v_lshlrev_b32_e32 v4, 16, v176
	v_and_b32_e32 v5, 0xffff0000, v176
	s_nop 2
	v_pk_add_f32 v[0:1], v[0:1], v[4:5]
	v_lshlrev_b32_e32 v4, 16, v178
	v_and_b32_e32 v5, 0xffff0000, v178
	v_pk_fma_f32 v[0:1], v[64:65], v[4:5], v[0:1]
	v_lshlrev_b32_e32 v4, 16, v177
	v_and_b32_e32 v5, 0xffff0000, v177
	v_pk_add_f32 v[2:3], v[2:3], v[4:5]
	v_lshlrev_b32_e32 v4, 16, v179
	v_and_b32_e32 v5, 0xffff0000, v179
	v_pk_fma_f32 v[2:3], v[66:67], v[4:5], v[2:3]
	v_pk_mul_f32 v[4:5], v[0:1], v[0:1]
	v_mov_b64_e32 v[6:7], s[22:23]
	v_pk_fma_f32 v[4:5], v[4:5], s[18:19], v[6:7] op_sel_hi:[1,0,0] neg_lo:[1,0,0] neg_hi:[1,0,0]
	v_pk_mul_f32 v[10:11], v[2:3], v[2:3]
	v_pk_mul_f32 v[4:5], v[0:1], v[4:5]
	v_pk_fma_f32 v[6:7], v[10:11], s[18:19], v[6:7] op_sel_hi:[1,0,0] neg_lo:[1,0,0] neg_hi:[1,0,0]
	v_exp_f32_e32 v4, v4
	v_exp_f32_e32 v5, v5
	v_pk_mul_f32 v[6:7], v[2:3], v[6:7]
	v_pk_add_f32 v[4:5], v[4:5], 1.0 op_sel_hi:[1,0]
	v_exp_f32_e32 v6, v6
	v_exp_f32_e32 v7, v7
	v_rcp_f32_e32 v4, v4
	v_rcp_f32_e32 v5, v5
	v_pk_add_f32 v[6:7], v[6:7], 1.0 op_sel_hi:[1,0]
	s_nop 0
	v_rcp_f32_e32 v6, v6
	v_rcp_f32_e32 v7, v7
	v_pk_mul_f32 v[0:1], v[0:1], v[4:5]
	v_pk_mul_f32 v[2:3], v[2:3], v[6:7]
	v_cvt_pk_bf16_f32 v4, v0, v1
	v_mul_f32_e32 v0, 0x3d924925, v0
	v_mul_f32_e32 v1, 0x3d924925, v1
	v_cvt_pk_bf16_f32 v5, v2, v3
	v_cvt_pknorm_i16_f32 v0, v0, v1
	v_mul_f32_e32 v1, 0x3d924925, v2
	v_mul_f32_e32 v2, 0x3d924925, v3
	v_cvt_pknorm_i16_f32 v1, v1, v2
	v_pk_add_i16 v0, v0, s54 op_sel_hi:[1,0] clamp
	v_pk_add_i16 v1, v1, s54 op_sel_hi:[1,0] clamp
	global_store_dwordx2 v[8:9], v[4:5], off
	v_perm_b32 v2, v1, v0, s55
	v_mov_b32_e32 v1, s7
	v_subrev_co_u32_e32 v0, vcc, s6, v8
	s_nop 1
	v_subb_co_u32_e32 v1, vcc, v9, v1, vcc
	v_ashrrev_i64 v[0:1], 1, v[0:1]
	v_bfe_u32 v1, v0, 4, 15
	v_lshlrev_b32_e32 v1, 6, v1
	v_bfi_b32 v0, s98, v1, v0
	v_lshrrev_b32_e32 v1, 15, v1
	v_bfi_b32 v0, 48, v1, v0
	global_store_dword v0, v2, s[8:9]
	v_add_co_u32_e32 v0, vcc, 0x4c3ff000, v198
	s_nop 1
	v_addc_co_u32_e32 v1, vcc, 0, v199, vcc
	v_add_co_u32_e32 v2, vcc, 0x2bbff000, v198
	s_nop 1
	v_addc_co_u32_e32 v3, vcc, 0, v199, vcc
	global_load_dwordx2 v[176:177], v[0:1], off offset:992
	global_load_dwordx2 v[178:179], v[2:3], off offset:992
	s_branch .LBB0_380

; #define LAS __attribute__((address_space(3)))
; __device__ __forceinline__ unsigned cvt_pk_bf16(float lo, float hi) { unsigned r; asm volatile("v_cvt_pk_bf16_f32 %0, %1, %2" : "=v"(r) : "v"(lo), "v"(hi)); return r; }
; template <bool REV> ...
;     ...
;         f32x16 acc[4];
; #pragma unroll
;         for (int i = 0; i < 4; ++i) { acc[i] = (f32x16){0.f,0.f,0.f,0.f,0.f,0.f,0.f,0.f,0.f,0.f,0.f,0.f,0.f,0.f,0.f,0.f};
;             acc[i] = __builtin_amdgcn_mfma_f32_32x32x16_bf16(A0, Bf[0][i], acc[i], 0, 0, 0); acc[i] = __builtin_amdgcn_mfma_f32_32x32x16_bf16(A1, Bf[1][i], acc[i], 0, 0, 0); }
;         A0 = *(const bf16x8*)(pA + adv); A1 = *(const bf16x8*)(pA + adv + 8);
;         float sre0[16], sre1[16], sim0[16], sim1[16];
; #pragma unroll
;         for (int r = 0; r < 16; ++r) {
;             auto s0 = __builtin_amdgcn_permlane32_swap(__float_as_uint(acc[0][r]), __float_as_uint(acc[2][r]), false, false);
;             auto s1 = __builtin_amdgcn_permlane32_swap(__float_as_uint(acc[1][r]), __float_as_uint(acc[3][r]), false, false);
;             sre0[r] = __uint_as_float(s0[0]); sre1[r] = __uint_as_float(s0[1]); sim0[r] = __uint_as_float(s1[0]); sim1[r] = __uint_as_float(s1[1]); }
; #pragma unroll
;         for (int i2 = 0; i2 < 16; ++i2) {
;             unsigned hw[2];
; #pragma unroll
;             for (int e = 0; e < 2; ++e) { const int i = 2 * i2 + e;
;                 const int r = (i & 3) + 4 * (i >> 3); const bool up = (i >> 2) & 1;
;                 const float sr = up ? sre1[r] : sre0[r], si = up ? sim1[r] : sim0[r];
;                 hw[e] = cvt_pk_bf16(hre, him);
;                 const float nre = __builtin_fmaf(lr, hre, __builtin_fmaf(nli, him, sr)), nim = __builtin_fmaf(lr, him, __builtin_fmaf(li, hre, si)); hre = nre; him = nim; }
;             LAS unsigned* wp = wbase + (2 * i2) * 64 + ((((lane >> 2) ^ (i2 & 15)) << 2));
;             wp[0] = hw[0]; wp[64] = hw[1];
;         }
.LBB0_400:
	s_waitcnt vmcnt(3)
	v_mfma_f32_32x32x16_bf16 v[48:63], v[152:155], v[108:111], 0
	s_mov_b64 s[0:1], 0x4c400000
	s_movk_i32 s16, 0xf7e0
	s_mov_b32 s17, -1
	v_mfma_f32_32x32x16_bf16 v[16:31], v[152:155], v[116:119], 0
	v_mfma_f32_32x32x16_bf16 v[32:47], v[152:155], v[112:115], 0
	v_mfma_f32_32x32x16_bf16 v[0:15], v[152:155], v[120:123], 0
	s_waitcnt vmcnt(2)
	v_mfma_f32_32x32x16_bf16 v[48:63], v[148:151], v[124:127], v[48:63]
	v_mfma_f32_32x32x16_bf16 v[16:31], v[148:151], v[132:135], v[16:31]
	v_mfma_f32_32x32x16_bf16 v[32:47], v[148:151], v[128:131], v[32:47]
	s_nop 10
	v_permlane32_swap_b32_e32 v48, v16
	v_permlane32_swap_b32_e32 v63, v31
	v_fma_f32 v31, -v157, v203, v48
	v_fmac_f32_e32 v31, v156, v202
	v_permlane32_swap_b32_e32 v49, v17
	v_mfma_f32_32x32x16_bf16 v[0:15], v[148:151], v[136:139], v[0:15]
	v_permlane32_swap_b32_e32 v50, v18
	v_permlane32_swap_b32_e32 v51, v19
	v_permlane32_swap_b32_e32 v52, v20
	v_permlane32_swap_b32_e32 v53, v21
	s_nop 7
	v_permlane32_swap_b32_e32 v32, v0
	v_permlane32_swap_b32_e32 v33, v1
	v_fmac_f32_e32 v32, v157, v202
	v_fmac_f32_e32 v32, v156, v203
	v_fmac_f32_e32 v33, v157, v31
	v_permlane32_swap_b32_e32 v47, v15
	v_fma_f32 v49, -v157, v32, v49
	v_fmac_f32_e32 v33, v156, v32
	v_permlane32_swap_b32_e32 v34, v2
	v_cvt_pk_bf16_f32 v15, v202, v203
	v_cvt_pk_bf16_f32 v48, v31, v32
	v_fmac_f32_e32 v49, v156, v31
	v_fma_f32 v31, -v157, v33, v50
	v_permlane32_swap_b32_e32 v35, v3
	v_fmac_f32_e32 v31, v156, v49
	v_fmac_f32_e32 v34, v157, v49
	v_fmac_f32_e32 v34, v156, v33
	v_fmac_f32_e32 v35, v157, v31
	ds_write2st64_b32 v248, v15, v48 offset1:1
	v_cvt_pk_bf16_f32 v15, v49, v33
	v_fma_f32 v33, -v157, v34, v51
	v_fmac_f32_e32 v35, v156, v34
	v_fmac_f32_e32 v33, v156, v31
	v_fma_f32 v16, -v157, v35, v16
	v_fmac_f32_e32 v16, v156, v33
	v_fmac_f32_e32 v0, v157, v33
	v_fmac_f32_e32 v0, v156, v35
	v_fmac_f32_e32 v1, v157, v16
	v_cvt_pk_bf16_f32 v32, v31, v34
	ds_write2st64_b32 v247, v15, v32 offset0:2 offset1:3
	v_cvt_pk_bf16_f32 v15, v33, v35
	v_fma_f32 v17, -v157, v0, v17
	v_fmac_f32_e32 v1, v156, v0
	v_cvt_pk_bf16_f32 v31, v16, v0
	v_fmac_f32_e32 v17, v156, v16
	ds_write2st64_b32 v246, v15, v31 offset0:4 offset1:5
	v_fma_f32 v15, -v157, v1, v18
	v_fmac_f32_e32 v15, v156, v17
	v_fmac_f32_e32 v2, v157, v17
	v_fmac_f32_e32 v2, v156, v1
	v_fmac_f32_e32 v3, v157, v15
	v_cvt_pk_bf16_f32 v0, v17, v1
	v_cvt_pk_bf16_f32 v1, v15, v2
	v_fma_f32 v16, -v157, v2, v19
	v_fmac_f32_e32 v3, v156, v2
	v_permlane32_swap_b32_e32 v36, v4
	v_fmac_f32_e32 v16, v156, v15
	ds_write2st64_b32 v245, v0, v1 offset0:6 offset1:7
	v_fma_f32 v1, -v157, v3, v52
	v_permlane32_swap_b32_e32 v37, v5
	v_fmac_f32_e32 v1, v156, v16
	v_fmac_f32_e32 v36, v157, v16
	v_fmac_f32_e32 v36, v156, v3
	v_fmac_f32_e32 v37, v157, v1
	v_permlane32_swap_b32_e32 v54, v22
	v_cvt_pk_bf16_f32 v0, v16, v3
	v_fma_f32 v3, -v157, v36, v53
	v_fmac_f32_e32 v37, v156, v36
	v_permlane32_swap_b32_e32 v38, v6
	v_cvt_pk_bf16_f32 v2, v1, v36
	v_fmac_f32_e32 v3, v156, v1
	v_fma_f32 v1, -v157, v37, v54
	v_permlane32_swap_b32_e32 v39, v7
	v_fmac_f32_e32 v1, v156, v3
	v_fmac_f32_e32 v38, v157, v3
	v_permlane32_swap_b32_e32 v55, v23
	v_fmac_f32_e32 v38, v156, v37
	v_fmac_f32_e32 v39, v157, v1
	ds_write2st64_b32 v244, v0, v2 offset0:8 offset1:9
	v_cvt_pk_bf16_f32 v0, v3, v37
	v_fma_f32 v3, -v157, v38, v55
	v_fmac_f32_e32 v39, v156, v38
	v_cvt_pk_bf16_f32 v2, v1, v38
	v_fmac_f32_e32 v3, v156, v1
	v_fma_f32 v1, -v157, v39, v20
	v_fmac_f32_e32 v1, v156, v3
	v_fmac_f32_e32 v4, v157, v3
	v_fmac_f32_e32 v4, v156, v39
	v_fmac_f32_e32 v5, v157, v1
	ds_write2st64_b32 v243, v0, v2 offset0:10 offset1:11
	v_cvt_pk_bf16_f32 v0, v3, v39
	v_fma_f32 v3, -v157, v4, v21
	v_fmac_f32_e32 v5, v156, v4
	v_cvt_pk_bf16_f32 v2, v1, v4
	v_fmac_f32_e32 v3, v156, v1
	v_fma_f32 v1, -v157, v5, v22
	v_fmac_f32_e32 v1, v156, v3
	v_fmac_f32_e32 v6, v157, v3
	v_fmac_f32_e32 v6, v156, v5
	v_fmac_f32_e32 v7, v157, v1
	v_permlane32_swap_b32_e32 v56, v24
	ds_write2st64_b32 v242, v0, v2 offset0:12 offset1:13
	v_cvt_pk_bf16_f32 v0, v3, v5
	v_fma_f32 v3, -v157, v6, v23
	v_fmac_f32_e32 v7, v156, v6
	v_permlane32_swap_b32_e32 v40, v8
	v_cvt_pk_bf16_f32 v2, v1, v6
	v_fmac_f32_e32 v3, v156, v1
	v_fma_f32 v1, -v157, v7, v56
	v_permlane32_swap_b32_e32 v41, v9
	v_fmac_f32_e32 v1, v156, v3
	v_fmac_f32_e32 v40, v157, v3
	v_permlane32_swap_b32_e32 v57, v25
	v_fmac_f32_e32 v40, v156, v7
	v_fmac_f32_e32 v41, v157, v1
	v_permlane32_swap_b32_e32 v58, v26
	ds_write2st64_b32 v241, v0, v2 offset0:14 offset1:15
	v_cvt_pk_bf16_f32 v0, v3, v7
	v_fma_f32 v3, -v157, v40, v57
	v_fmac_f32_e32 v41, v156, v40
	v_permlane32_swap_b32_e32 v42, v10
	v_cvt_pk_bf16_f32 v2, v1, v40
	v_fmac_f32_e32 v3, v156, v1
	v_fma_f32 v1, -v157, v41, v58
	v_permlane32_swap_b32_e32 v43, v11
	v_fmac_f32_e32 v1, v156, v3
	v_fmac_f32_e32 v42, v157, v3
	v_permlane32_swap_b32_e32 v59, v27
	v_fmac_f32_e32 v42, v156, v41
	v_fmac_f32_e32 v43, v157, v1
	ds_write2st64_b32 v240, v0, v2 offset0:16 offset1:17
	v_cvt_pk_bf16_f32 v0, v3, v41
	v_fma_f32 v3, -v157, v42, v59
	v_fmac_f32_e32 v43, v156, v42
	v_cvt_pk_bf16_f32 v2, v1, v42
	v_fmac_f32_e32 v3, v156, v1
	v_fma_f32 v1, -v157, v43, v24
	v_fmac_f32_e32 v1, v156, v3
	v_fmac_f32_e32 v8, v157, v3
	v_fmac_f32_e32 v8, v156, v43
	v_fmac_f32_e32 v9, v157, v1
	ds_write2st64_b32 v239, v0, v2 offset0:18 offset1:19
	v_cvt_pk_bf16_f32 v0, v3, v43
	v_fma_f32 v3, -v157, v8, v25
	v_fmac_f32_e32 v9, v156, v8
	v_cvt_pk_bf16_f32 v2, v1, v8
	v_fmac_f32_e32 v3, v156, v1
	v_fma_f32 v1, -v157, v9, v26
	v_fmac_f32_e32 v1, v156, v3
	v_fmac_f32_e32 v10, v157, v3
	v_fmac_f32_e32 v10, v156, v9
	v_fmac_f32_e32 v11, v157, v1
	v_permlane32_swap_b32_e32 v60, v28
; #define LAS __attribute__((address_space(3)))
; __device__ __forceinline__ unsigned cvt_pk_bf16(float lo, float hi) { unsigned r; asm volatile("v_cvt_pk_bf16_f32 %0, %1, %2" : "=v"(r) : "v"(lo), "v"(hi)); return r; }
; __device__ __forceinline__ unsigned cvt_pk_bf16_mfma(float lo, float hi) { unsigned r; asm volatile("s_nop 7\n\ts_nop 4\n\tv_cvt_pk_bf16_f32 %0, %1, %2" : "=v"(r) : "v"(lo), "v"(hi)); return r; }
; __device__ __forceinline__ float bf_lo(unsigned w) { return __uint_as_float(w << 16); }
; __device__ __forceinline__ float bf_hi(unsigned w) { return __uint_as_float(w & 0xffff0000u); }
; template <bool REV> ...
;     ...
; #pragma unroll
;         for (int th = 0; th < 2; ++th) {
;             bf16x8 Hf[4];
; #pragma unroll
;             for (int ks = 0; ks < 4; ++ks) Hf[ks] = *(const LAS bf16x8*)(my + (16 * th + tk) * 256 + ((((4 * ks + kq) ^ ((8 * th + (tk >> 1)) & 15))) << 4));
; #pragma unroll
;             for (int sx = 0; sx < 2; ++sx) {
;                 f32x4 y = (f32x4){0.f, 0.f, 0.f, 0.f};
;                 y = __builtin_amdgcn_mfma_f32_16x16x32_bf16(Kf[sx], Ub[th], y, 0, 0, 0);
; #pragma unroll
;                 for (int ks = 0; ks < 4; ++ks) y = __builtin_amdgcn_mfma_f32_16x16x32_bf16(Cf[sx][ks], Hf[ks], y, 0, 0, 0);
;                 bf16* yo = pY + th * CSTEP16 + sx * SSTEP;
;                 if (!second) { u32x2 w; w.x = cvt_pk_bf16_mfma(y[0], y[1]); w.y = cvt_pk_bf16(y[2], y[3]); *(u32x2*)yo = w; }
;                 else { const u32x2 p = pv[th][sx], u = uv[th][sx];
;                     const f32x2 v01 = (f32x2){y[0], y[1]} + (f32x2){bf_lo(p.x), bf_hi(p.x)} + dsk01 * (f32x2){bf_lo(u.x), bf_hi(u.x)};
;                     const f32x2 v23 = (f32x2){y[2], y[3]} + (f32x2){bf_lo(p.y), bf_hi(p.y)} + dsk23 * (f32x2){bf_lo(u.y), bf_hi(u.y)};
;                     const f32x2 o01 = gelu2(v01), o23 = gelu2(v23);
;                     u32x2 w; w.x = cvt_pk_bf16(o01.x, o01.y); w.y = cvt_pk_bf16(o23.x, o23.y); *(u32x2*)yo = w;
;                     { const unsigned x8 = pack_i8x4(o01.x, o01.y, o23.x, o23.y, 1.0f / YA8_R);
;                       *(unsigned*)(Y8 + (yo - YA)) = x8; }
;                     pv[th][sx] = *(const u32x2*)(yo + adv); uv[th][sx] = *(const u32x2*)(pU + th * CSTEP16 + sx * SSTEP + adv); }
	ds_write2st64_b32 v238, v0, v2 offset0:20 offset1:21
	v_cvt_pk_bf16_f32 v0, v3, v9
	v_fma_f32 v3, -v157, v10, v27
	v_fmac_f32_e32 v11, v156, v10
	v_permlane32_swap_b32_e32 v44, v12
	v_cvt_pk_bf16_f32 v2, v1, v10
	v_fmac_f32_e32 v3, v156, v1
	v_fma_f32 v1, -v157, v11, v60
	v_permlane32_swap_b32_e32 v45, v13
	v_fmac_f32_e32 v1, v156, v3
	v_fmac_f32_e32 v44, v157, v3
	v_permlane32_swap_b32_e32 v61, v29
	v_fmac_f32_e32 v44, v156, v11
	v_fmac_f32_e32 v45, v157, v1
	v_permlane32_swap_b32_e32 v62, v30
	ds_write2st64_b32 v237, v0, v2 offset0:22 offset1:23
	v_cvt_pk_bf16_f32 v0, v3, v11
	v_fma_f32 v3, -v157, v44, v61
	v_fmac_f32_e32 v45, v156, v44
	v_permlane32_swap_b32_e32 v46, v14
	v_cvt_pk_bf16_f32 v2, v1, v44
	v_fmac_f32_e32 v3, v156, v1
	v_fma_f32 v1, -v157, v45, v62
	v_fmac_f32_e32 v1, v156, v3
	v_fmac_f32_e32 v46, v157, v3
	v_fmac_f32_e32 v46, v156, v45
	v_fmac_f32_e32 v47, v157, v1
	ds_write2st64_b32 v232, v0, v2 offset0:24 offset1:25
	v_cvt_pk_bf16_f32 v0, v3, v45
	v_fma_f32 v3, -v157, v46, v63
	v_fmac_f32_e32 v47, v156, v46
	v_cvt_pk_bf16_f32 v2, v1, v46
	v_fmac_f32_e32 v3, v156, v1
	v_fma_f32 v1, -v157, v47, v28
	v_fmac_f32_e32 v1, v156, v3
	v_fmac_f32_e32 v12, v157, v3
	v_fmac_f32_e32 v12, v156, v47
	v_fmac_f32_e32 v13, v157, v1
	ds_write2st64_b32 v231, v0, v2 offset0:26 offset1:27
	v_cvt_pk_bf16_f32 v0, v3, v47
	v_fma_f32 v3, -v157, v12, v29
	v_fmac_f32_e32 v13, v156, v12
	v_cvt_pk_bf16_f32 v2, v1, v12
	v_fmac_f32_e32 v3, v156, v1
	v_fma_f32 v1, -v157, v13, v30
	v_fmac_f32_e32 v1, v156, v3
	v_fmac_f32_e32 v14, v157, v3
	ds_write2st64_b32 v230, v0, v2 offset0:28 offset1:29
	v_cvt_pk_bf16_f32 v0, v3, v13
	v_fmac_f32_e32 v14, v156, v13
	v_cvt_pk_bf16_f32 v1, v1, v14
	ds_write2st64_b32 v229, v0, v1 offset0:30 offset1:31
	s_waitcnt vmcnt(1)
	v_mfma_f32_16x16x32_bf16 v[0:3], v[104:107], v[144:147], 0
	ds_read_b128 v[4:7], v235
	ds_read_b128 v[8:11], v236
	ds_read_b128 v[12:15], v234
	ds_read_b128 v[16:19], v233
	s_waitcnt lgkmcnt(3)
	v_mfma_f32_16x16x32_bf16 v[0:3], v[88:91], v[4:7], v[0:3]
	v_lshlrev_b32_e32 v22, 16, v192
	v_and_b32_e32 v23, 0xffff0000, v192
	v_lshl_add_u64 v[20:21], v[184:185], 0, s[12:13]
	s_waitcnt lgkmcnt(2)
	v_mfma_f32_16x16x32_bf16 v[0:3], v[92:95], v[8:11], v[0:3]
	s_mov_b32 s12, 0xc0135761
	v_lshl_add_u64 v[24:25], v[20:21], 0, s[0:1]
	s_mov_b32 s0, 0x3dd2d3e8
	s_waitcnt lgkmcnt(1)
	v_mfma_f32_16x16x32_bf16 v[0:3], v[96:99], v[12:15], v[0:3]
	s_waitcnt lgkmcnt(0)
	v_mfma_f32_16x16x32_bf16 v[0:3], v[100:103], v[16:19], v[0:3]
	s_nop 7
	v_pk_add_f32 v[0:1], v[0:1], v[22:23]
	v_lshlrev_b32_e32 v22, 16, v190
	v_and_b32_e32 v23, 0xffff0000, v190
	v_pk_fma_f32 v[22:23], v[64:65], v[22:23], v[0:1]
	v_lshlrev_b32_e32 v0, 16, v193
	v_and_b32_e32 v1, 0xffff0000, v193
	v_pk_add_f32 v[0:1], v[2:3], v[0:1]
	v_lshlrev_b32_e32 v2, 16, v191
	v_and_b32_e32 v3, 0xffff0000, v191
	v_pk_fma_f32 v[26:27], v[66:67], v[2:3], v[0:1]
	v_pk_mul_f32 v[0:1], v[22:23], v[22:23]
	v_mov_b64_e32 v[2:3], s[12:13]
	v_pk_fma_f32 v[0:1], v[0:1], s[0:1], v[2:3] op_sel_hi:[1,0,0] neg_lo:[1,0,0] neg_hi:[1,0,0]
	v_pk_mul_f32 v[28:29], v[26:27], v[26:27]
	v_pk_mul_f32 v[0:1], v[22:23], v[0:1]
	v_pk_fma_f32 v[28:29], v[28:29], s[0:1], v[2:3] op_sel_hi:[1,0,0] neg_lo:[1,0,0] neg_hi:[1,0,0]
	v_exp_f32_e32 v0, v0
	v_exp_f32_e32 v1, v1
	v_pk_mul_f32 v[28:29], v[26:27], v[28:29]
	s_mov_b64 s[12:13], 0x4c400800
	v_exp_f32_e32 v28, v28
	v_exp_f32_e32 v29, v29
	v_pk_add_f32 v[0:1], v[0:1], 1.0 op_sel_hi:[1,0]
	s_mov_b32 s1, 0x4c400000
	v_rcp_f32_e32 v30, v0
	v_rcp_f32_e32 v31, v1
	v_pk_add_f32 v[0:1], v[28:29], 1.0 op_sel_hi:[1,0]
	v_pk_mul_f32 v[22:23], v[22:23], v[30:31]
	v_rcp_f32_e32 v28, v0
	v_rcp_f32_e32 v29, v1
	v_lshl_add_u64 v[0:1], v[20:21], 0, s[12:13]
	v_add_co_u32_e32 v20, vcc, s1, v20
	v_pk_mul_f32 v[26:27], v[26:27], v[28:29]
	s_nop 0
	v_addc_co_u32_e32 v21, vcc, 0, v21, vcc
	v_cvt_pk_bf16_f32 v28, v22, v23
	v_cvt_pk_bf16_f32 v29, v26, v27
	global_store_dwordx2 v[20:21], v[28:29], off
	v_mul_f32_e32 v20, 0x3d924925, v22
	v_mul_f32_e32 v21, 0x3d924925, v23
	v_cvt_pknorm_i16_f32 v28, v20, v21
	v_mul_f32_e32 v20, 0x3d924925, v26
	v_mul_f32_e32 v21, 0x3d924925, v27
	v_cvt_pknorm_i16_f32 v26, v20, v21
	v_mfma_f32_16x16x32_bf16 v[20:23], v[84:87], v[144:147], 0
	s_movk_i32 s1, 0x80
	v_pk_add_i16 v27, v28, s1 op_sel_hi:[1,0] clamp
	v_pk_add_i16 v26, v26, s1 op_sel_hi:[1,0] clamp
	v_mfma_f32_16x16x32_bf16 v[4:7], v[68:71], v[4:7], v[20:23]
	s_mov_b32 s12, 0x7050301
	v_mfma_f32_16x16x32_bf16 v[4:7], v[72:75], v[8:11], v[4:7]
	s_nop 1
	v_mov_b32_e32 v21, s7
	v_subrev_co_u32_e32 v8, vcc, s6, v24
	v_mfma_f32_16x16x32_bf16 v[4:7], v[76:79], v[12:15], v[4:7]
	s_nop 0
	v_subb_co_u32_e32 v9, vcc, v25, v21, vcc
	v_ashrrev_i64 v[8:9], 1, v[8:9]
	v_mfma_f32_16x16x32_bf16 v[4:7], v[80:83], v[16:19], v[4:7]
	v_perm_b32 v20, v26, v27, s12
	v_bfe_u32 v9, v8, 4, 15
	v_lshlrev_b32_e32 v9, 6, v9
	v_bfi_b32 v8, s98, v9, v8
	v_lshrrev_b32_e32 v9, 15, v9
	v_bfi_b32 v8, 48, v9, v8
	global_store_dword v8, v20, s[8:9]
	v_lshlrev_b32_e32 v8, 16, v188
	v_and_b32_e32 v9, 0xffff0000, v188
	s_nop 2
	v_pk_add_f32 v[4:5], v[4:5], v[8:9]
	v_lshlrev_b32_e32 v8, 16, v186
	v_and_b32_e32 v9, 0xffff0000, v186
	v_pk_fma_f32 v[4:5], v[64:65], v[8:9], v[4:5]
	v_lshlrev_b32_e32 v8, 16, v189
	v_and_b32_e32 v9, 0xffff0000, v189
	v_pk_add_f32 v[6:7], v[6:7], v[8:9]
	v_lshlrev_b32_e32 v8, 16, v187
	v_and_b32_e32 v9, 0xffff0000, v187
	v_pk_fma_f32 v[6:7], v[66:67], v[8:9], v[6:7]
	v_pk_mul_f32 v[8:9], v[4:5], v[4:5]
	v_pk_mul_f32 v[10:11], v[6:7], v[6:7]
	v_pk_fma_f32 v[8:9], v[8:9], s[0:1], v[2:3] op_sel_hi:[1,0,0] neg_lo:[1,0,0] neg_hi:[1,0,0]
	v_pk_fma_f32 v[10:11], v[10:11], s[0:1], v[2:3] op_sel_hi:[1,0,0] neg_lo:[1,0,0] neg_hi:[1,0,0]
	v_pk_mul_f32 v[8:9], v[4:5], v[8:9]
	v_pk_mul_f32 v[10:11], v[6:7], v[10:11]
	v_exp_f32_e32 v8, v8
	v_exp_f32_e32 v9, v9
	v_exp_f32_e32 v10, v10
	v_exp_f32_e32 v11, v11
	s_waitcnt vmcnt(2)
; #define LAS __attribute__((address_space(3)))
; __device__ __forceinline__ unsigned cvt_pk_bf16(float lo, float hi) { unsigned r; asm volatile("v_cvt_pk_bf16_f32 %0, %1, %2" : "=v"(r) : "v"(lo), "v"(hi)); return r; }
; __device__ __forceinline__ unsigned cvt_pk_bf16_mfma(float lo, float hi) { unsigned r; asm volatile("s_nop 7\n\ts_nop 4\n\tv_cvt_pk_bf16_f32 %0, %1, %2" : "=v"(r) : "v"(lo), "v"(hi)); return r; }
; __device__ __forceinline__ float bf_lo(unsigned w) { return __uint_as_float(w << 16); }
; __device__ __forceinline__ float bf_hi(unsigned w) { return __uint_as_float(w & 0xffff0000u); }
; template <bool REV> ...
;     ...
;         for (int th = 0; th < 2; ++th) {
;             bf16x8 Hf[4];
; #pragma unroll
;             for (int ks = 0; ks < 4; ++ks) Hf[ks] = *(const LAS bf16x8*)(my + (16 * th + tk) * 256 + ((((4 * ks + kq) ^ ((8 * th + (tk >> 1)) & 15))) << 4));
; #pragma unroll
;             for (int sx = 0; sx < 2; ++sx) {
;                 f32x4 y = (f32x4){0.f, 0.f, 0.f, 0.f};
;                 y = __builtin_amdgcn_mfma_f32_16x16x32_bf16(Kf[sx], Ub[th], y, 0, 0, 0);
; #pragma unroll
;                 for (int ks = 0; ks < 4; ++ks) y = __builtin_amdgcn_mfma_f32_16x16x32_bf16(Cf[sx][ks], Hf[ks], y, 0, 0, 0);
;                 bf16* yo = pY + th * CSTEP16 + sx * SSTEP;
;                 if (!second) { u32x2 w; w.x = cvt_pk_bf16_mfma(y[0], y[1]); w.y = cvt_pk_bf16(y[2], y[3]); *(u32x2*)yo = w; }
;                 else { const u32x2 p = pv[th][sx], u = uv[th][sx];
;                     const f32x2 v01 = (f32x2){y[0], y[1]} + (f32x2){bf_lo(p.x), bf_hi(p.x)} + dsk01 * (f32x2){bf_lo(u.x), bf_hi(u.x)};
;                     const f32x2 v23 = (f32x2){y[2], y[3]} + (f32x2){bf_lo(p.y), bf_hi(p.y)} + dsk23 * (f32x2){bf_lo(u.y), bf_hi(u.y)};
;                     const f32x2 o01 = gelu2(v01), o23 = gelu2(v23);
;                     u32x2 w; w.x = cvt_pk_bf16(o01.x, o01.y); w.y = cvt_pk_bf16(o23.x, o23.y); *(u32x2*)yo = w;
;                     { const unsigned x8 = pack_i8x4(o01.x, o01.y, o23.x, o23.y, 1.0f / YA8_R);
;                       *(unsigned*)(Y8 + (yo - YA)) = x8; }
;                     pv[th][sx] = *(const u32x2*)(yo + adv); uv[th][sx] = *(const u32x2*)(pU + th * CSTEP16 + sx * SSTEP + adv); }
;             }
;             Ub[th] = *(const bf16x8*)(pB + th * CSTEP16 + adv);
;         }
;         pA += adv; pB += adv; pU += adv; pY += adv;
	v_mfma_f32_16x16x32_bf16 v[12:15], v[104:107], v[140:143], 0
	v_add_f32_e64 v8, v8, 1.0
	v_add_f32_e64 v9, v9, 1.0
	v_lshl_add_u64 v[24:25], v[0:1], 0, s[16:17]
	v_rcp_f32_e32 v8, v8
	v_rcp_f32_e32 v9, v9
	v_pk_add_f32 v[10:11], v[10:11], 1.0 op_sel_hi:[1,0]
	v_mov_b32_e32 v27, s7
	v_rcp_f32_e32 v10, v10
	v_rcp_f32_e32 v11, v11
	v_pk_mul_f32 v[4:5], v[4:5], v[8:9]
	v_subrev_co_u32_e32 v24, vcc, s6, v24
	v_pk_mul_f32 v[6:7], v[6:7], v[10:11]
	v_cvt_pk_bf16_f32 v8, v4, v5
	v_mul_f32_e32 v4, 0x3d924925, v4
	v_mul_f32_e32 v5, 0x3d924925, v5
	v_cvt_pk_bf16_f32 v9, v6, v7
	global_store_dwordx2 v[0:1], v[8:9], off offset:-2080
	v_cvt_pknorm_i16_f32 v16, v4, v5
	v_mul_f32_e32 v4, 0x3d924925, v6
	v_mul_f32_e32 v5, 0x3d924925, v7
	v_cvt_pknorm_i16_f32 v17, v4, v5
	ds_read_b128 v[4:7], v171 offset:4096
	ds_read_b128 v[8:11], v169 offset:4096
	s_waitcnt lgkmcnt(0)
	v_mfma_f32_16x16x32_bf16 v[12:15], v[88:91], v[8:11], v[12:15]
	v_pk_add_i16 v16, v16, s1 op_sel_hi:[1,0] clamp
	v_pk_add_i16 v17, v17, s1 op_sel_hi:[1,0] clamp
	v_subb_co_u32_e32 v25, vcc, v25, v27, vcc
	v_perm_b32 v26, v17, v16, s12
	ds_read_b128 v[16:19], v167 offset:4096
	ds_read_b128 v[20:23], v163 offset:4096
	v_mfma_f32_16x16x32_bf16 v[12:15], v[92:95], v[4:7], v[12:15]
	v_ashrrev_i64 v[24:25], 1, v[24:25]
	v_bfe_u32 v25, v24, 4, 15
	v_lshlrev_b32_e32 v25, 6, v25
	v_bfi_b32 v24, s98, v25, v24
	v_lshrrev_b32_e32 v25, 15, v25
	v_bfi_b32 v24, 48, v25, v24
	global_store_dword v24, v26, s[8:9]
	s_waitcnt lgkmcnt(0)
	v_mfma_f32_16x16x32_bf16 v[12:15], v[96:99], v[20:23], v[12:15]
	v_lshlrev_b32_e32 v24, 16, v180
	v_and_b32_e32 v25, 0xffff0000, v180
	s_movk_i32 s16, 0xf400
	v_mfma_f32_16x16x32_bf16 v[12:15], v[100:103], v[16:19], v[12:15]
	s_mov_b32 s17, -1
	v_lshl_add_u64 v[28:29], v[0:1], 0, s[16:17]
	s_nop 5
	v_pk_add_f32 v[12:13], v[12:13], v[24:25]
	v_lshlrev_b32_e32 v24, 16, v182
	v_and_b32_e32 v25, 0xffff0000, v182
	v_pk_fma_f32 v[12:13], v[64:65], v[24:25], v[12:13]
	v_lshlrev_b32_e32 v24, 16, v181
	v_and_b32_e32 v25, 0xffff0000, v181
	v_pk_add_f32 v[14:15], v[14:15], v[24:25]
	v_lshlrev_b32_e32 v24, 16, v183
	v_and_b32_e32 v25, 0xffff0000, v183
	v_pk_fma_f32 v[14:15], v[66:67], v[24:25], v[14:15]
	v_pk_mul_f32 v[24:25], v[12:13], v[12:13]
	v_pk_mul_f32 v[26:27], v[14:15], v[14:15]
	v_pk_fma_f32 v[24:25], v[24:25], s[0:1], v[2:3] op_sel_hi:[1,0,0] neg_lo:[1,0,0] neg_hi:[1,0,0]
	v_pk_fma_f32 v[26:27], v[26:27], s[0:1], v[2:3] op_sel_hi:[1,0,0] neg_lo:[1,0,0] neg_hi:[1,0,0]
	v_pk_mul_f32 v[24:25], v[12:13], v[24:25]
	v_pk_mul_f32 v[26:27], v[14:15], v[26:27]
	v_exp_f32_e32 v24, v24
	v_exp_f32_e32 v25, v25
	v_exp_f32_e32 v26, v26
	v_exp_f32_e32 v27, v27
	v_pk_add_f32 v[24:25], v[24:25], 1.0 op_sel_hi:[1,0]
	s_nop 0
	v_rcp_f32_e32 v24, v24
	v_rcp_f32_e32 v25, v25
	v_pk_add_f32 v[26:27], v[26:27], 1.0 op_sel_hi:[1,0]
	v_pk_mul_f32 v[12:13], v[12:13], v[24:25]
	v_rcp_f32_e32 v26, v26
	v_rcp_f32_e32 v27, v27
	s_nop 0
	v_pk_mul_f32 v[24:25], v[14:15], v[26:27]
	v_cvt_pk_bf16_f32 v14, v12, v13
	s_nop 0
	v_cvt_pk_bf16_f32 v15, v24, v25
	v_mul_f32_e32 v12, 0x3d924925, v12
	v_mul_f32_e32 v13, 0x3d924925, v13
	global_store_dwordx2 v[0:1], v[14:15], off offset:-3072
	v_cvt_pknorm_i16_f32 v26, v12, v13
	v_mfma_f32_16x16x32_bf16 v[12:15], v[84:87], v[140:143], 0
	v_mul_f32_e32 v24, 0x3d924925, v24
	v_mul_f32_e32 v25, 0x3d924925, v25
	v_cvt_pknorm_i16_f32 v24, v24, v25
	v_mfma_f32_16x16x32_bf16 v[8:11], v[68:71], v[8:11], v[12:15]
	v_pk_add_i16 v25, v26, s1 op_sel_hi:[1,0] clamp
	v_mfma_f32_16x16x32_bf16 v[4:7], v[72:75], v[4:7], v[8:11]
	s_nop 1
	v_mov_b32_e32 v13, s7
	v_pk_add_i16 v12, v24, s1 op_sel_hi:[1,0] clamp
	v_mfma_f32_16x16x32_bf16 v[4:7], v[76:79], v[20:23], v[4:7]
	s_nop 0
	v_subrev_co_u32_e32 v8, vcc, s6, v28
	v_perm_b32 v12, v12, v25, s12
	s_nop 0
	v_subb_co_u32_e32 v9, vcc, v29, v13, vcc
	v_mfma_f32_16x16x32_bf16 v[4:7], v[80:83], v[16:19], v[4:7]
	v_ashrrev_i64 v[8:9], 1, v[8:9]
	v_bfe_u32 v9, v8, 4, 15
	v_lshlrev_b32_e32 v9, 6, v9
	v_bfi_b32 v8, s98, v9, v8
	v_lshrrev_b32_e32 v9, 15, v9
	v_bfi_b32 v8, 48, v9, v8
	global_store_dword v8, v12, s[8:9]
	v_lshlrev_b32_e32 v8, 16, v176
	v_and_b32_e32 v9, 0xffff0000, v176
	s_nop 2
	v_pk_add_f32 v[4:5], v[4:5], v[8:9]
	v_lshlrev_b32_e32 v8, 16, v178
	v_and_b32_e32 v9, 0xffff0000, v178
	v_pk_fma_f32 v[4:5], v[64:65], v[8:9], v[4:5]
	v_lshlrev_b32_e32 v8, 16, v177
	v_and_b32_e32 v9, 0xffff0000, v177
	v_pk_add_f32 v[6:7], v[6:7], v[8:9]
	v_lshlrev_b32_e32 v8, 16, v179
	v_and_b32_e32 v9, 0xffff0000, v179
	v_pk_fma_f32 v[6:7], v[66:67], v[8:9], v[6:7]
	v_pk_mul_f32 v[8:9], v[4:5], v[4:5]
	v_pk_mul_f32 v[10:11], v[6:7], v[6:7]
	v_pk_fma_f32 v[8:9], v[8:9], s[0:1], v[2:3] op_sel_hi:[1,0,0] neg_lo:[1,0,0] neg_hi:[1,0,0]
	v_pk_fma_f32 v[2:3], v[10:11], s[0:1], v[2:3] op_sel_hi:[1,0,0] neg_lo:[1,0,0] neg_hi:[1,0,0]
	v_pk_mul_f32 v[8:9], v[4:5], v[8:9]
	v_pk_mul_f32 v[2:3], v[6:7], v[2:3]
	v_exp_f32_e32 v8, v8
	v_exp_f32_e32 v9, v9
	v_exp_f32_e32 v2, v2
	v_exp_f32_e32 v3, v3
	s_movk_i32 s0, 0xf3e0
	v_pk_add_f32 v[8:9], v[8:9], 1.0 op_sel_hi:[1,0]
	s_mov_b32 s1, -1
	v_pk_add_f32 v[2:3], v[2:3], 1.0 op_sel_hi:[1,0]
	v_rcp_f32_e32 v8, v8
	v_rcp_f32_e32 v9, v9
	v_rcp_f32_e32 v10, v2
	v_rcp_f32_e32 v11, v3
	v_lshl_add_u64 v[2:3], v[0:1], 0, s[0:1]
	v_pk_mul_f32 v[4:5], v[4:5], v[8:9]
	v_pk_mul_f32 v[6:7], v[6:7], v[10:11]
	v_cvt_pk_bf16_f32 v8, v4, v5
	s_nop 0
	v_cvt_pk_bf16_f32 v9, v6, v7
	global_store_dwordx2 v[0:1], v[8:9], off offset:-3104
	s_branch .LBB0_422

; __device__ __forceinline__ unsigned cvt_pk_bf16(float lo, float hi) { unsigned r; asm volatile("v_cvt_pk_bf16_f32 %0, %1, %2" : "=v"(r) : "v"(lo), "v"(hi)); return r; }
; __device__ __forceinline__ float bf_lo(unsigned w) { return __uint_as_float(w << 16); }
; __device__ __forceinline__ float bf_hi(unsigned w) { return __uint_as_float(w & 0xffff0000u); }
; template <bool REV> ...
;     ...
;                 else { const u32x2 p = pv[th][sx], u = uv[th][sx];
;                     const f32x2 v01 = (f32x2){y[0], y[1]} + (f32x2){bf_lo(p.x), bf_hi(p.x)} + dsk01 * (f32x2){bf_lo(u.x), bf_hi(u.x)};
;                     const f32x2 v23 = (f32x2){y[2], y[3]} + (f32x2){bf_lo(p.y), bf_hi(p.y)} + dsk23 * (f32x2){bf_lo(u.y), bf_hi(u.y)};
;                     const f32x2 o01 = gelu2(v01), o23 = gelu2(v23);
;                     u32x2 w; w.x = cvt_pk_bf16(o01.x, o01.y); w.y = cvt_pk_bf16(o23.x, o23.y); *(u32x2*)yo = w;
;                     { const unsigned x8 = pack_i8x4(o01.x, o01.y, o23.x, o23.y, 1.0f / YA8_R);
;                       *(unsigned*)(Y8 + (yo - YA)) = x8; }
;                     pv[th][sx] = *(const u32x2*)(yo + adv); uv[th][sx] = *(const u32x2*)(pU + th * CSTEP16 + sx * SSTEP + adv); }
.LBB0_407:
	s_andn2_b64 vcc, exec, s[0:1]
	s_cbranch_vccnz .LBB0_409
	v_lshlrev_b32_e32 v24, 16, v180
	v_and_b32_e32 v25, 0xffff0000, v180
	s_nop 2
	v_pk_add_f32 v[20:21], v[20:21], v[24:25]
	v_lshlrev_b32_e32 v24, 16, v178
	v_and_b32_e32 v25, 0xffff0000, v178
	v_pk_fma_f32 v[20:21], v[64:65], v[24:25], v[20:21]
	v_lshlrev_b32_e32 v24, 16, v181
	v_and_b32_e32 v25, 0xffff0000, v181
	v_pk_add_f32 v[22:23], v[22:23], v[24:25]
	v_lshlrev_b32_e32 v24, 16, v179
	v_and_b32_e32 v25, 0xffff0000, v179
	v_pk_fma_f32 v[22:23], v[66:67], v[24:25], v[22:23]
	v_pk_mul_f32 v[24:25], v[20:21], v[20:21]
	v_mov_b64_e32 v[26:27], s[18:19]
	v_pk_fma_f32 v[24:25], v[24:25], s[16:17], v[26:27] op_sel_hi:[1,0,0] neg_lo:[1,0,0] neg_hi:[1,0,0]
	v_pk_mul_f32 v[28:29], v[22:23], v[22:23]
	v_pk_mul_f32 v[24:25], v[20:21], v[24:25]
	v_pk_fma_f32 v[26:27], v[28:29], s[16:17], v[26:27] op_sel_hi:[1,0,0] neg_lo:[1,0,0] neg_hi:[1,0,0]
	v_exp_f32_e32 v24, v24
	v_exp_f32_e32 v25, v25
	v_pk_mul_f32 v[26:27], v[22:23], v[26:27]
	v_pk_add_f32 v[24:25], v[24:25], 1.0 op_sel_hi:[1,0]
	v_exp_f32_e32 v26, v26
	v_exp_f32_e32 v27, v27
	v_rcp_f32_e32 v24, v24
	v_rcp_f32_e32 v25, v25
	v_pk_add_f32 v[26:27], v[26:27], 1.0 op_sel_hi:[1,0]
	s_nop 0
	v_rcp_f32_e32 v26, v26
	v_rcp_f32_e32 v27, v27
	v_pk_mul_f32 v[20:21], v[20:21], v[24:25]
	v_pk_mul_f32 v[22:23], v[22:23], v[26:27]
	v_cvt_pk_bf16_f32 v24, v20, v21
	v_mul_f32_e32 v14, 0x3d924925, v20
	v_mul_f32_e32 v20, 0x3d924925, v21
	v_cvt_pknorm_i16_f32 v14, v14, v20
	v_mul_f32_e32 v20, 0x3d924925, v22
	v_mul_f32_e32 v21, 0x3d924925, v23
	v_cvt_pknorm_i16_f32 v20, v20, v21
	v_pk_add_i16 v14, v14, s33 op_sel_hi:[1,0] clamp
	v_pk_add_i16 v20, v20, s33 op_sel_hi:[1,0] clamp
	v_mov_b32_e32 v21, s7
	v_perm_b32 v14, v20, v14, s34
	v_subrev_co_u32_e32 v20, vcc, s6, v188
	v_cvt_pk_bf16_f32 v25, v22, v23
	global_store_dwordx2 v[188:189], v[24:25], off
	s_nop 0
	v_subb_co_u32_e32 v21, vcc, v189, v21, vcc
	v_ashrrev_i64 v[20:21], 1, v[20:21]
	v_bfe_u32 v21, v20, 4, 15
	v_lshlrev_b32_e32 v21, 6, v21
	v_bfi_b32 v20, s98, v21, v20
	v_lshrrev_b32_e32 v21, 15, v21
	v_bfi_b32 v20, 48, v21, v20
	global_store_dword v20, v14, s[8:9]
	v_add_co_u32_e32 v20, vcc, 0x4c400000, v186
	s_nop 1
	v_addc_co_u32_e32 v21, vcc, 0, v187, vcc
	v_add_co_u32_e32 v22, vcc, 0x2bc00000, v186
	s_nop 1
	v_addc_co_u32_e32 v23, vcc, 0, v187, vcc
	global_load_dwordx2 v[180:181], v[20:21], off offset:2048
	global_load_dwordx2 v[178:179], v[22:23], off offset:2048

; __device__ __forceinline__ unsigned cvt_pk_bf16(float lo, float hi) { unsigned r; asm volatile("v_cvt_pk_bf16_f32 %0, %1, %2" : "=v"(r) : "v"(lo), "v"(hi)); return r; }
; __device__ __forceinline__ float bf_lo(unsigned w) { return __uint_as_float(w << 16); }
; __device__ __forceinline__ float bf_hi(unsigned w) { return __uint_as_float(w & 0xffff0000u); }
; template <bool REV> ...
;     ...
;                 else { const u32x2 p = pv[th][sx], u = uv[th][sx];
;                     const f32x2 v01 = (f32x2){y[0], y[1]} + (f32x2){bf_lo(p.x), bf_hi(p.x)} + dsk01 * (f32x2){bf_lo(u.x), bf_hi(u.x)};
;                     const f32x2 v23 = (f32x2){y[2], y[3]} + (f32x2){bf_lo(p.y), bf_hi(p.y)} + dsk23 * (f32x2){bf_lo(u.y), bf_hi(u.y)};
;                     const f32x2 o01 = gelu2(v01), o23 = gelu2(v23);
;                     u32x2 w; w.x = cvt_pk_bf16(o01.x, o01.y); w.y = cvt_pk_bf16(o23.x, o23.y); *(u32x2*)yo = w;
;                     { const unsigned x8 = pack_i8x4(o01.x, o01.y, o23.x, o23.y, 1.0f / YA8_R);
;                       *(unsigned*)(Y8 + (yo - YA)) = x8; }
;                     pv[th][sx] = *(const u32x2*)(yo + adv); uv[th][sx] = *(const u32x2*)(pU + th * CSTEP16 + sx * SSTEP + adv); }
.LBB0_411:
	s_andn2_b64 vcc, exec, s[46:47]
	s_cbranch_vccnz .LBB0_413
	v_lshlrev_b32_e32 v4, 16, v176
	v_and_b32_e32 v5, 0xffff0000, v176
	s_nop 2
	v_pk_add_f32 v[0:1], v[0:1], v[4:5]
	v_lshlrev_b32_e32 v4, 16, v172
	v_and_b32_e32 v5, 0xffff0000, v172
	v_pk_fma_f32 v[0:1], v[64:65], v[4:5], v[0:1]
	v_lshlrev_b32_e32 v4, 16, v177
	v_and_b32_e32 v5, 0xffff0000, v177
	v_pk_add_f32 v[2:3], v[2:3], v[4:5]
	v_lshlrev_b32_e32 v4, 16, v173
	v_and_b32_e32 v5, 0xffff0000, v173
	v_pk_fma_f32 v[2:3], v[66:67], v[4:5], v[2:3]
	v_pk_mul_f32 v[4:5], v[0:1], v[0:1]
	v_mov_b64_e32 v[6:7], s[18:19]
	v_pk_fma_f32 v[4:5], v[4:5], s[16:17], v[6:7] op_sel_hi:[1,0,0] neg_lo:[1,0,0] neg_hi:[1,0,0]
	v_pk_mul_f32 v[10:11], v[2:3], v[2:3]
	v_pk_mul_f32 v[4:5], v[0:1], v[4:5]
	v_pk_fma_f32 v[6:7], v[10:11], s[16:17], v[6:7] op_sel_hi:[1,0,0] neg_lo:[1,0,0] neg_hi:[1,0,0]
	v_exp_f32_e32 v4, v4
	v_exp_f32_e32 v5, v5
	v_pk_mul_f32 v[6:7], v[2:3], v[6:7]
	v_pk_add_f32 v[4:5], v[4:5], 1.0 op_sel_hi:[1,0]
	v_exp_f32_e32 v6, v6
	v_exp_f32_e32 v7, v7
	v_rcp_f32_e32 v4, v4
	v_rcp_f32_e32 v5, v5
	v_pk_add_f32 v[6:7], v[6:7], 1.0 op_sel_hi:[1,0]
	s_nop 0
	v_rcp_f32_e32 v6, v6
	v_rcp_f32_e32 v7, v7
	v_pk_mul_f32 v[0:1], v[0:1], v[4:5]
	v_pk_mul_f32 v[2:3], v[2:3], v[6:7]
	v_cvt_pk_bf16_f32 v4, v0, v1
	v_mul_f32_e32 v0, 0x3d924925, v0
	v_mul_f32_e32 v1, 0x3d924925, v1
	v_cvt_pk_bf16_f32 v5, v2, v3
	v_cvt_pknorm_i16_f32 v0, v0, v1
	v_mul_f32_e32 v1, 0x3d924925, v2
	v_mul_f32_e32 v2, 0x3d924925, v3
	v_cvt_pknorm_i16_f32 v1, v1, v2
	v_pk_add_i16 v0, v0, s33 op_sel_hi:[1,0] clamp
	v_pk_add_i16 v1, v1, s33 op_sel_hi:[1,0] clamp
	global_store_dwordx2 v[8:9], v[4:5], off
	v_perm_b32 v2, v1, v0, s34
	v_mov_b32_e32 v1, s7
	v_subrev_co_u32_e32 v0, vcc, s6, v8
	s_nop 1
	v_subb_co_u32_e32 v1, vcc, v9, v1, vcc
	v_ashrrev_i64 v[0:1], 1, v[0:1]
	v_bfe_u32 v1, v0, 4, 15
	v_lshlrev_b32_e32 v1, 6, v1
	v_bfi_b32 v0, s98, v1, v0
	v_lshrrev_b32_e32 v1, 15, v1
	v_bfi_b32 v0, 48, v1, v0
	global_store_dword v0, v2, s[8:9]
	v_add_co_u32_e32 v0, vcc, 0x4c400000, v186
	s_nop 1
	v_addc_co_u32_e32 v1, vcc, 0, v187, vcc
	v_add_co_u32_e32 v2, vcc, 0x2bc00000, v186
	s_nop 1
	v_addc_co_u32_e32 v3, vcc, 0, v187, vcc
	global_load_dwordx2 v[176:177], v[0:1], off offset:2080
	global_load_dwordx2 v[172:173], v[2:3], off offset:2080

; __device__ __forceinline__ unsigned cvt_pk_bf16(float lo, float hi) { unsigned r; asm volatile("v_cvt_pk_bf16_f32 %0, %1, %2" : "=v"(r) : "v"(lo), "v"(hi)); return r; }
; __device__ __forceinline__ float bf_lo(unsigned w) { return __uint_as_float(w << 16); }
; __device__ __forceinline__ float bf_hi(unsigned w) { return __uint_as_float(w & 0xffff0000u); }
; template <bool REV> ...
;     ...
;                 else { const u32x2 p = pv[th][sx], u = uv[th][sx];
;                     const f32x2 v01 = (f32x2){y[0], y[1]} + (f32x2){bf_lo(p.x), bf_hi(p.x)} + dsk01 * (f32x2){bf_lo(u.x), bf_hi(u.x)};
;                     const f32x2 v23 = (f32x2){y[2], y[3]} + (f32x2){bf_lo(p.y), bf_hi(p.y)} + dsk23 * (f32x2){bf_lo(u.y), bf_hi(u.y)};
;                     const f32x2 o01 = gelu2(v01), o23 = gelu2(v23);
;                     u32x2 w; w.x = cvt_pk_bf16(o01.x, o01.y); w.y = cvt_pk_bf16(o23.x, o23.y); *(u32x2*)yo = w;
;                     { const unsigned x8 = pack_i8x4(o01.x, o01.y, o23.x, o23.y, 1.0f / YA8_R);
;                       *(unsigned*)(Y8 + (yo - YA)) = x8; }
;                     pv[th][sx] = *(const u32x2*)(yo + adv); uv[th][sx] = *(const u32x2*)(pU + th * CSTEP16 + sx * SSTEP + adv); }
.LBB0_415:
	s_andn2_b64 vcc, exec, s[42:43]
	s_cbranch_vccnz .LBB0_417
	v_lshlrev_b32_e32 v28, 16, v170
	v_and_b32_e32 v29, 0xffff0000, v170
	s_nop 2
	v_pk_add_f32 v[20:21], v[20:21], v[28:29]
	v_lshlrev_b32_e32 v28, 16, v168
	v_and_b32_e32 v29, 0xffff0000, v168
	v_pk_fma_f32 v[20:21], v[64:65], v[28:29], v[20:21]
	v_lshlrev_b32_e32 v28, 16, v171
	v_and_b32_e32 v29, 0xffff0000, v171
	v_pk_add_f32 v[22:23], v[22:23], v[28:29]
	v_lshlrev_b32_e32 v28, 16, v169
	v_and_b32_e32 v29, 0xffff0000, v169
	v_pk_fma_f32 v[22:23], v[66:67], v[28:29], v[22:23]
	v_pk_mul_f32 v[28:29], v[20:21], v[20:21]
	v_mov_b64_e32 v[32:33], s[18:19]
	v_pk_fma_f32 v[28:29], v[28:29], s[16:17], v[32:33] op_sel_hi:[1,0,0] neg_lo:[1,0,0] neg_hi:[1,0,0]
	v_pk_mul_f32 v[34:35], v[22:23], v[22:23]
	v_pk_mul_f32 v[28:29], v[20:21], v[28:29]
	v_pk_fma_f32 v[32:33], v[34:35], s[16:17], v[32:33] op_sel_hi:[1,0,0] neg_lo:[1,0,0] neg_hi:[1,0,0]
	v_exp_f32_e32 v28, v28
	v_exp_f32_e32 v29, v29
	v_pk_mul_f32 v[32:33], v[22:23], v[32:33]
	v_pk_add_f32 v[28:29], v[28:29], 1.0 op_sel_hi:[1,0]
	v_exp_f32_e32 v32, v32
	v_exp_f32_e32 v33, v33
	v_rcp_f32_e32 v28, v28
	v_rcp_f32_e32 v29, v29
	v_pk_add_f32 v[32:33], v[32:33], 1.0 op_sel_hi:[1,0]
	s_nop 0
	v_rcp_f32_e32 v32, v32
	v_rcp_f32_e32 v33, v33
	v_pk_mul_f32 v[20:21], v[20:21], v[28:29]
	v_pk_mul_f32 v[22:23], v[22:23], v[32:33]
	v_cvt_pk_bf16_f32 v28, v20, v21
	v_mul_f32_e32 v14, 0x3d924925, v20
	v_mul_f32_e32 v20, 0x3d924925, v21
	v_cvt_pknorm_i16_f32 v14, v14, v20
	v_mul_f32_e32 v20, 0x3d924925, v22
	v_mul_f32_e32 v21, 0x3d924925, v23
	v_cvt_pknorm_i16_f32 v20, v20, v21
	v_pk_add_i16 v14, v14, s33 op_sel_hi:[1,0] clamp
	v_pk_add_i16 v20, v20, s33 op_sel_hi:[1,0] clamp
	v_mov_b32_e32 v21, s7
	v_perm_b32 v14, v20, v14, s34
	v_subrev_co_u32_e32 v20, vcc, s6, v26
	v_cvt_pk_bf16_f32 v29, v22, v23
	global_store_dwordx2 v[26:27], v[28:29], off
	s_nop 0
	v_subb_co_u32_e32 v21, vcc, v27, v21, vcc
	v_ashrrev_i64 v[20:21], 1, v[20:21]
	v_bfe_u32 v21, v20, 4, 15
	v_lshlrev_b32_e32 v21, 6, v21
	v_bfi_b32 v20, s98, v21, v20
	v_lshrrev_b32_e32 v21, 15, v21
	v_bfi_b32 v20, 48, v21, v20
	global_store_dword v20, v14, s[8:9]
	v_add_co_u32_e32 v20, vcc, 0x4c400000, v186
	s_nop 1
	v_addc_co_u32_e32 v21, vcc, 0, v187, vcc
	v_add_co_u32_e32 v22, vcc, 0x2bc00000, v186
	s_nop 1
	v_addc_co_u32_e32 v23, vcc, 0, v187, vcc
	global_load_dwordx2 v[170:171], v[20:21], off offset:3072
	global_load_dwordx2 v[168:169], v[22:23], off offset:3072

; template <bool REV> ...
;     ...
;         f32x16 acc[4];
; #pragma unroll
;         for (int i = 0; i < 4; ++i) { acc[i] = (f32x16){0.f,0.f,0.f,0.f,0.f,0.f,0.f,0.f,0.f,0.f,0.f,0.f,0.f,0.f,0.f,0.f};
;             acc[i] = __builtin_amdgcn_mfma_f32_32x32x16_bf16(A0, Bf[0][i], acc[i], 0, 0, 0); acc[i] = __builtin_amdgcn_mfma_f32_32x32x16_bf16(A1, Bf[1][i], acc[i], 0, 0, 0); }
;         A0 = *(const bf16x8*)(pA + adv); A1 = *(const bf16x8*)(pA + adv + 8);
;         float sre0[16], sre1[16], sim0[16], sim1[16];
; #pragma unroll
;         for (int r = 0; r < 16; ++r) {
;             auto s0 = __builtin_amdgcn_permlane32_swap(__float_as_uint(acc[0][r]), __float_as_uint(acc[2][r]), false, false);
;             auto s1 = __builtin_amdgcn_permlane32_swap(__float_as_uint(acc[1][r]), __float_as_uint(acc[3][r]), false, false);
;             sre0[r] = __uint_as_float(s0[0]); sre1[r] = __uint_as_float(s0[1]); sim0[r] = __uint_as_float(s1[0]); sim1[r] = __uint_as_float(s1[1]); }
; #pragma unroll
;         for (int i2 = 0; i2 < 16; ++i2) {
;             unsigned hw[2];
; #pragma unroll
;             for (int e = 0; e < 2; ++e) { const int i = 2 * i2 + e;
;                 const int r = (i & 3) + 4 * (i >> 3); const bool up = (i >> 2) & 1;
;                 const float sr = up ? sre1[r] : sre0[r], si = up ? sim1[r] : sim0[r];
;                 hw[e] = cvt_pk_bf16(hre, him);
;                 const float nre = __builtin_fmaf(lr, hre, __builtin_fmaf(nli, him, sr)), nim = __builtin_fmaf(lr, him, __builtin_fmaf(li, hre, si)); hre = nre; him = nim; }
;     ...
;                 else { const u32x2 p = pv[th][sx], u = uv[th][sx];
;                     const f32x2 v01 = (f32x2){y[0], y[1]} + (f32x2){bf_lo(p.x), bf_hi(p.x)} + dsk01 * (f32x2){bf_lo(u.x), bf_hi(u.x)};
;                     const f32x2 v23 = (f32x2){y[2], y[3]} + (f32x2){bf_lo(p.y), bf_hi(p.y)} + dsk23 * (f32x2){bf_lo(u.y), bf_hi(u.y)};
;                     const f32x2 o01 = gelu2(v01), o23 = gelu2(v23);
;                     u32x2 w; w.x = cvt_pk_bf16(o01.x, o01.y); w.y = cvt_pk_bf16(o23.x, o23.y); *(u32x2*)yo = w;
;                     { const unsigned x8 = pack_i8x4(o01.x, o01.y, o23.x, o23.y, 1.0f / YA8_R);
;                       *(unsigned*)(Y8 + (yo - YA)) = x8; }
;                     pv[th][sx] = *(const u32x2*)(yo + adv); uv[th][sx] = *(const u32x2*)(pU + th * CSTEP16 + sx * SSTEP + adv); }
.LBB0_419:
	s_andn2_b64 vcc, exec, s[42:43]
	s_cbranch_vccnz .LBB0_402
	v_lshlrev_b32_e32 v4, 16, v162
	v_and_b32_e32 v5, 0xffff0000, v162
	s_nop 2
	v_pk_add_f32 v[0:1], v[0:1], v[4:5]
	v_lshlrev_b32_e32 v4, 16, v166
	v_and_b32_e32 v5, 0xffff0000, v166
	v_pk_fma_f32 v[0:1], v[64:65], v[4:5], v[0:1]
	v_lshlrev_b32_e32 v4, 16, v163
	v_and_b32_e32 v5, 0xffff0000, v163
	v_pk_add_f32 v[2:3], v[2:3], v[4:5]
	v_lshlrev_b32_e32 v4, 16, v167
	v_and_b32_e32 v5, 0xffff0000, v167
	v_pk_fma_f32 v[2:3], v[66:67], v[4:5], v[2:3]
	v_pk_mul_f32 v[4:5], v[0:1], v[0:1]
	v_mov_b64_e32 v[6:7], s[18:19]
	v_pk_fma_f32 v[4:5], v[4:5], s[16:17], v[6:7] op_sel_hi:[1,0,0] neg_lo:[1,0,0] neg_hi:[1,0,0]
	v_pk_mul_f32 v[10:11], v[2:3], v[2:3]
	v_pk_mul_f32 v[4:5], v[0:1], v[4:5]
	v_pk_fma_f32 v[6:7], v[10:11], s[16:17], v[6:7] op_sel_hi:[1,0,0] neg_lo:[1,0,0] neg_hi:[1,0,0]
	v_exp_f32_e32 v4, v4
	v_exp_f32_e32 v5, v5
	v_pk_mul_f32 v[6:7], v[2:3], v[6:7]
	v_pk_add_f32 v[4:5], v[4:5], 1.0 op_sel_hi:[1,0]
	v_exp_f32_e32 v6, v6
	v_exp_f32_e32 v7, v7
	v_rcp_f32_e32 v4, v4
	v_rcp_f32_e32 v5, v5
	v_pk_add_f32 v[6:7], v[6:7], 1.0 op_sel_hi:[1,0]
	s_nop 0
	v_rcp_f32_e32 v6, v6
	v_rcp_f32_e32 v7, v7
	v_pk_mul_f32 v[0:1], v[0:1], v[4:5]
	v_pk_mul_f32 v[2:3], v[2:3], v[6:7]
	v_cvt_pk_bf16_f32 v4, v0, v1
	v_mul_f32_e32 v0, 0x3d924925, v0
	v_mul_f32_e32 v1, 0x3d924925, v1
	v_cvt_pk_bf16_f32 v5, v2, v3
	v_cvt_pknorm_i16_f32 v0, v0, v1
	v_mul_f32_e32 v1, 0x3d924925, v2
	v_mul_f32_e32 v2, 0x3d924925, v3
	v_cvt_pknorm_i16_f32 v1, v1, v2
	v_pk_add_i16 v0, v0, s33 op_sel_hi:[1,0] clamp
	v_pk_add_i16 v1, v1, s33 op_sel_hi:[1,0] clamp
	global_store_dwordx2 v[8:9], v[4:5], off
	v_perm_b32 v2, v1, v0, s34
	v_mov_b32_e32 v1, s7
	v_subrev_co_u32_e32 v0, vcc, s6, v8
	s_nop 1
	v_subb_co_u32_e32 v1, vcc, v9, v1, vcc
	v_ashrrev_i64 v[0:1], 1, v[0:1]
	v_bfe_u32 v1, v0, 4, 15
	v_lshlrev_b32_e32 v1, 6, v1
	v_bfi_b32 v0, s98, v1, v0
	v_lshrrev_b32_e32 v1, 15, v1
	v_bfi_b32 v0, 48, v1, v0
	global_store_dword v0, v2, s[8:9]
	v_add_co_u32_e32 v0, vcc, 0x4c400000, v186
	s_nop 1
	v_addc_co_u32_e32 v1, vcc, 0, v187, vcc
	v_add_co_u32_e32 v2, vcc, 0x2bc00000, v186
	s_nop 1
	v_addc_co_u32_e32 v3, vcc, 0, v187, vcc
	global_load_dwordx2 v[162:163], v[0:1], off offset:3104
	global_load_dwordx2 v[166:167], v[2:3], off offset:3104
	s_branch .LBB0_402
.LBB0_421:
	s_waitcnt vmcnt(3)
	v_mfma_f32_32x32x16_bf16 v[48:63], v[152:155], v[108:111], 0
	s_mov_b64 s[0:1], 0x4c400000
	s_mov_b64 s[12:13], 0x820
	v_mfma_f32_32x32x16_bf16 v[16:31], v[152:155], v[116:119], 0
	v_mfma_f32_32x32x16_bf16 v[32:47], v[152:155], v[112:115], 0
	v_mfma_f32_32x32x16_bf16 v[0:15], v[152:155], v[120:123], 0
	s_waitcnt vmcnt(2)
	v_mfma_f32_32x32x16_bf16 v[48:63], v[148:151], v[124:127], v[48:63]
	v_mfma_f32_32x32x16_bf16 v[16:31], v[148:151], v[132:135], v[16:31]
	v_mfma_f32_32x32x16_bf16 v[32:47], v[148:151], v[128:131], v[32:47]
	s_nop 10
	v_permlane32_swap_b32_e32 v48, v16
	v_permlane32_swap_b32_e32 v63, v31
	v_fma_f32 v31, -v157, v164, v48
	v_fmac_f32_e32 v31, v156, v165
	v_permlane32_swap_b32_e32 v49, v17
	v_mfma_f32_32x32x16_bf16 v[0:15], v[148:151], v[136:139], v[0:15]
	v_permlane32_swap_b32_e32 v50, v18
	v_permlane32_swap_b32_e32 v51, v19
	v_permlane32_swap_b32_e32 v52, v20
	v_permlane32_swap_b32_e32 v53, v21
	s_nop 7
	v_permlane32_swap_b32_e32 v32, v0
	v_permlane32_swap_b32_e32 v33, v1
	v_fmac_f32_e32 v32, v157, v165
	v_fmac_f32_e32 v32, v156, v164
	v_fmac_f32_e32 v33, v157, v31
	v_permlane32_swap_b32_e32 v47, v15
	v_fma_f32 v49, -v157, v32, v49
	v_fmac_f32_e32 v33, v156, v32
	v_permlane32_swap_b32_e32 v34, v2
	v_cvt_pk_bf16_f32 v15, v165, v164
	v_cvt_pk_bf16_f32 v48, v31, v32
	v_fmac_f32_e32 v49, v156, v31
	v_fma_f32 v31, -v157, v33, v50
	v_permlane32_swap_b32_e32 v35, v3
	v_fmac_f32_e32 v31, v156, v49
	v_fmac_f32_e32 v34, v157, v49
	v_fmac_f32_e32 v34, v156, v33
	v_fmac_f32_e32 v35, v157, v31
	ds_write2st64_b32 v232, v15, v48 offset1:1
	v_cvt_pk_bf16_f32 v15, v49, v33
	v_fma_f32 v33, -v157, v34, v51
	v_fmac_f32_e32 v35, v156, v34
	v_fmac_f32_e32 v33, v156, v31
	v_fma_f32 v16, -v157, v35, v16
	v_fmac_f32_e32 v16, v156, v33
	v_fmac_f32_e32 v0, v157, v33
	v_fmac_f32_e32 v0, v156, v35
	v_fmac_f32_e32 v1, v157, v16
	v_cvt_pk_bf16_f32 v32, v31, v34
	ds_write2st64_b32 v231, v15, v32 offset0:2 offset1:3
	v_cvt_pk_bf16_f32 v15, v33, v35
	v_fma_f32 v17, -v157, v0, v17
	v_fmac_f32_e32 v1, v156, v0
	v_cvt_pk_bf16_f32 v31, v16, v0
	v_fmac_f32_e32 v17, v156, v16
	ds_write2st64_b32 v230, v15, v31 offset0:4 offset1:5
	v_fma_f32 v15, -v157, v1, v18
	v_fmac_f32_e32 v15, v156, v17
	v_fmac_f32_e32 v2, v157, v17
	v_fmac_f32_e32 v2, v156, v1
	v_fmac_f32_e32 v3, v157, v15
	v_cvt_pk_bf16_f32 v0, v17, v1
	v_cvt_pk_bf16_f32 v1, v15, v2
	v_fma_f32 v16, -v157, v2, v19
	v_fmac_f32_e32 v3, v156, v2
	v_permlane32_swap_b32_e32 v36, v4
	v_fmac_f32_e32 v16, v156, v15
	ds_write2st64_b32 v229, v0, v1 offset0:6 offset1:7
	v_fma_f32 v1, -v157, v3, v52
	v_permlane32_swap_b32_e32 v37, v5
	v_fmac_f32_e32 v1, v156, v16
	v_fmac_f32_e32 v36, v157, v16
	v_fmac_f32_e32 v36, v156, v3
	v_fmac_f32_e32 v37, v157, v1
	v_permlane32_swap_b32_e32 v54, v22
	v_cvt_pk_bf16_f32 v0, v16, v3
	v_fma_f32 v3, -v157, v36, v53
	v_fmac_f32_e32 v37, v156, v36
	v_permlane32_swap_b32_e32 v38, v6
	v_cvt_pk_bf16_f32 v2, v1, v36
	v_fmac_f32_e32 v3, v156, v1
	v_fma_f32 v1, -v157, v37, v54
	v_permlane32_swap_b32_e32 v39, v7
	v_fmac_f32_e32 v1, v156, v3
	v_fmac_f32_e32 v38, v157, v3
	v_permlane32_swap_b32_e32 v55, v23
	v_fmac_f32_e32 v38, v156, v37
	v_fmac_f32_e32 v39, v157, v1
	ds_write2st64_b32 v216, v0, v2 offset0:8 offset1:9
	v_cvt_pk_bf16_f32 v0, v3, v37
	v_fma_f32 v3, -v157, v38, v55
; #define LAS __attribute__((address_space(3)))
; __device__ __forceinline__ unsigned cvt_pk_bf16(float lo, float hi) { unsigned r; asm volatile("v_cvt_pk_bf16_f32 %0, %1, %2" : "=v"(r) : "v"(lo), "v"(hi)); return r; }
; template <bool REV> ...
;     ...
;         for (int i2 = 0; i2 < 16; ++i2) {
;             unsigned hw[2];
; #pragma unroll
;             for (int e = 0; e < 2; ++e) { const int i = 2 * i2 + e;
;                 const int r = (i & 3) + 4 * (i >> 3); const bool up = (i >> 2) & 1;
;                 const float sr = up ? sre1[r] : sre0[r], si = up ? sim1[r] : sim0[r];
;                 hw[e] = cvt_pk_bf16(hre, him);
;                 const float nre = __builtin_fmaf(lr, hre, __builtin_fmaf(nli, him, sr)), nim = __builtin_fmaf(lr, him, __builtin_fmaf(li, hre, si)); hre = nre; him = nim; }
;             LAS unsigned* wp = wbase + (2 * i2) * 64 + ((((lane >> 2) ^ (i2 & 15)) << 2));
;             wp[0] = hw[0]; wp[64] = hw[1];
;         }
; #pragma unroll
;         for (int th = 0; th < 2; ++th) {
;             bf16x8 Hf[4];
; #pragma unroll
;             for (int ks = 0; ks < 4; ++ks) Hf[ks] = *(const LAS bf16x8*)(my + (16 * th + tk) * 256 + ((((4 * ks + kq) ^ ((8 * th + (tk >> 1)) & 15))) << 4));
; #pragma unroll
;             for (int sx = 0; sx < 2; ++sx) {
;                 f32x4 y = (f32x4){0.f, 0.f, 0.f, 0.f};
;                 y = __builtin_amdgcn_mfma_f32_16x16x32_bf16(Kf[sx], Ub[th], y, 0, 0, 0);
; #pragma unroll
;                 for (int ks = 0; ks < 4; ++ks) y = __builtin_amdgcn_mfma_f32_16x16x32_bf16(Cf[sx][ks], Hf[ks], y, 0, 0, 0);
	v_fmac_f32_e32 v39, v156, v38
	v_cvt_pk_bf16_f32 v2, v1, v38
	v_fmac_f32_e32 v3, v156, v1
	v_fma_f32 v1, -v157, v39, v20
	v_fmac_f32_e32 v1, v156, v3
	v_fmac_f32_e32 v4, v157, v3
	v_fmac_f32_e32 v4, v156, v39
	v_fmac_f32_e32 v5, v157, v1
	ds_write2st64_b32 v215, v0, v2 offset0:10 offset1:11
	v_cvt_pk_bf16_f32 v0, v3, v39
	v_fma_f32 v3, -v157, v4, v21
	v_fmac_f32_e32 v5, v156, v4
	v_cvt_pk_bf16_f32 v2, v1, v4
	v_fmac_f32_e32 v3, v156, v1
	v_fma_f32 v1, -v157, v5, v22
	v_fmac_f32_e32 v1, v156, v3
	v_fmac_f32_e32 v6, v157, v3
	v_fmac_f32_e32 v6, v156, v5
	v_fmac_f32_e32 v7, v157, v1
	v_permlane32_swap_b32_e32 v56, v24
	ds_write2st64_b32 v214, v0, v2 offset0:12 offset1:13
	v_cvt_pk_bf16_f32 v0, v3, v5
	v_fma_f32 v3, -v157, v6, v23
	v_fmac_f32_e32 v7, v156, v6
	v_permlane32_swap_b32_e32 v40, v8
	v_cvt_pk_bf16_f32 v2, v1, v6
	v_fmac_f32_e32 v3, v156, v1
	v_fma_f32 v1, -v157, v7, v56
	v_permlane32_swap_b32_e32 v41, v9
	v_fmac_f32_e32 v1, v156, v3
	v_fmac_f32_e32 v40, v157, v3
	v_permlane32_swap_b32_e32 v57, v25
	v_fmac_f32_e32 v40, v156, v7
	v_fmac_f32_e32 v41, v157, v1
	v_permlane32_swap_b32_e32 v58, v26
	ds_write2st64_b32 v213, v0, v2 offset0:14 offset1:15
	v_cvt_pk_bf16_f32 v0, v3, v7
	v_fma_f32 v3, -v157, v40, v57
	v_fmac_f32_e32 v41, v156, v40
	v_permlane32_swap_b32_e32 v42, v10
	v_cvt_pk_bf16_f32 v2, v1, v40
	v_fmac_f32_e32 v3, v156, v1
	v_fma_f32 v1, -v157, v41, v58
	v_permlane32_swap_b32_e32 v43, v11
	v_fmac_f32_e32 v1, v156, v3
	v_fmac_f32_e32 v42, v157, v3
	v_permlane32_swap_b32_e32 v59, v27
	v_fmac_f32_e32 v42, v156, v41
	v_fmac_f32_e32 v43, v157, v1
	ds_write2st64_b32 v212, v0, v2 offset0:16 offset1:17
	v_cvt_pk_bf16_f32 v0, v3, v41
	v_fma_f32 v3, -v157, v42, v59
	v_fmac_f32_e32 v43, v156, v42
	v_cvt_pk_bf16_f32 v2, v1, v42
	v_fmac_f32_e32 v3, v156, v1
	v_fma_f32 v1, -v157, v43, v24
	v_fmac_f32_e32 v1, v156, v3
	v_fmac_f32_e32 v8, v157, v3
	v_fmac_f32_e32 v8, v156, v43
	v_fmac_f32_e32 v9, v157, v1
	ds_write2st64_b32 v204, v0, v2 offset0:18 offset1:19
	v_cvt_pk_bf16_f32 v0, v3, v43
	v_fma_f32 v3, -v157, v8, v25
	v_fmac_f32_e32 v9, v156, v8
	v_cvt_pk_bf16_f32 v2, v1, v8
	v_fmac_f32_e32 v3, v156, v1
	v_fma_f32 v1, -v157, v9, v26
	v_fmac_f32_e32 v1, v156, v3
	v_fmac_f32_e32 v10, v157, v3
	v_fmac_f32_e32 v10, v156, v9
	v_fmac_f32_e32 v11, v157, v1
	v_permlane32_swap_b32_e32 v60, v28
	ds_write2st64_b32 v203, v0, v2 offset0:20 offset1:21
	v_cvt_pk_bf16_f32 v0, v3, v9
	v_fma_f32 v3, -v157, v10, v27
	v_fmac_f32_e32 v11, v156, v10
	v_permlane32_swap_b32_e32 v44, v12
	v_cvt_pk_bf16_f32 v2, v1, v10
	v_fmac_f32_e32 v3, v156, v1
	v_fma_f32 v1, -v157, v11, v60
	v_permlane32_swap_b32_e32 v45, v13
	v_fmac_f32_e32 v1, v156, v3
	v_fmac_f32_e32 v44, v157, v3
	v_permlane32_swap_b32_e32 v61, v29
	v_fmac_f32_e32 v44, v156, v11
	v_fmac_f32_e32 v45, v157, v1
	v_permlane32_swap_b32_e32 v62, v30
	ds_write2st64_b32 v202, v0, v2 offset0:22 offset1:23
	v_cvt_pk_bf16_f32 v0, v3, v11
	v_fma_f32 v3, -v157, v44, v61
	v_fmac_f32_e32 v45, v156, v44
	v_permlane32_swap_b32_e32 v46, v14
	v_cvt_pk_bf16_f32 v2, v1, v44
	v_fmac_f32_e32 v3, v156, v1
	v_fma_f32 v1, -v157, v45, v62
	v_fmac_f32_e32 v1, v156, v3
	v_fmac_f32_e32 v46, v157, v3
	v_fmac_f32_e32 v46, v156, v45
	v_fmac_f32_e32 v47, v157, v1
	ds_write2st64_b32 v197, v0, v2 offset0:24 offset1:25
	v_cvt_pk_bf16_f32 v0, v3, v45
	v_fma_f32 v3, -v157, v46, v63
	v_fmac_f32_e32 v47, v156, v46
	v_cvt_pk_bf16_f32 v2, v1, v46
	v_fmac_f32_e32 v3, v156, v1
	v_fma_f32 v1, -v157, v47, v28
	v_fmac_f32_e32 v1, v156, v3
	v_fmac_f32_e32 v12, v157, v3
	v_fmac_f32_e32 v12, v156, v47
	v_fmac_f32_e32 v13, v157, v1
	ds_write2st64_b32 v196, v0, v2 offset0:26 offset1:27
	v_cvt_pk_bf16_f32 v0, v3, v47
	v_fma_f32 v3, -v157, v12, v29
	v_fmac_f32_e32 v13, v156, v12
	v_cvt_pk_bf16_f32 v2, v1, v12
	v_fmac_f32_e32 v3, v156, v1
	v_fma_f32 v1, -v157, v13, v30
	v_fmac_f32_e32 v1, v156, v3
	v_fmac_f32_e32 v14, v157, v3
	ds_write2st64_b32 v195, v0, v2 offset0:28 offset1:29
	v_cvt_pk_bf16_f32 v0, v3, v13
	v_fmac_f32_e32 v14, v156, v13
	v_cvt_pk_bf16_f32 v1, v1, v14
	ds_write2st64_b32 v194, v0, v1 offset0:30 offset1:31
	s_waitcnt vmcnt(1)
	v_mfma_f32_16x16x32_bf16 v[0:3], v[104:107], v[144:147], 0
	ds_read_b128 v[4:7], v200
	ds_read_b128 v[8:11], v201
	ds_read_b128 v[12:15], v199
	ds_read_b128 v[16:19], v198
	s_waitcnt lgkmcnt(3)
	v_mfma_f32_16x16x32_bf16 v[0:3], v[88:91], v[4:7], v[0:3]
	v_lshlrev_b32_e32 v22, 16, v180
	v_and_b32_e32 v23, 0xffff0000, v180
	v_lshl_add_u64 v[20:21], v[174:175], 0, s[10:11]
	s_waitcnt lgkmcnt(2)
	v_mfma_f32_16x16x32_bf16 v[0:3], v[92:95], v[8:11], v[0:3]
	s_mov_b32 s10, 0xc0135761
	v_lshl_add_u64 v[24:25], v[20:21], 0, s[0:1]
	s_mov_b32 s0, 0x3dd2d3e8
	s_waitcnt lgkmcnt(1)
	v_mfma_f32_16x16x32_bf16 v[0:3], v[96:99], v[12:15], v[0:3]
	s_waitcnt lgkmcnt(0)
; __device__ __forceinline__ unsigned cvt_pk_bf16(float lo, float hi) { unsigned r; asm volatile("v_cvt_pk_bf16_f32 %0, %1, %2" : "=v"(r) : "v"(lo), "v"(hi)); return r; }
; __device__ __forceinline__ unsigned cvt_pk_bf16_mfma(float lo, float hi) { unsigned r; asm volatile("s_nop 7\n\ts_nop 4\n\tv_cvt_pk_bf16_f32 %0, %1, %2" : "=v"(r) : "v"(lo), "v"(hi)); return r; }
; __device__ __forceinline__ float bf_lo(unsigned w) { return __uint_as_float(w << 16); }
; __device__ __forceinline__ float bf_hi(unsigned w) { return __uint_as_float(w & 0xffff0000u); }
; template <bool REV> ...
;     ...
;                 f32x4 y = (f32x4){0.f, 0.f, 0.f, 0.f};
;                 y = __builtin_amdgcn_mfma_f32_16x16x32_bf16(Kf[sx], Ub[th], y, 0, 0, 0);
; #pragma unroll
;                 for (int ks = 0; ks < 4; ++ks) y = __builtin_amdgcn_mfma_f32_16x16x32_bf16(Cf[sx][ks], Hf[ks], y, 0, 0, 0);
;                 bf16* yo = pY + th * CSTEP16 + sx * SSTEP;
;                 if (!second) { u32x2 w; w.x = cvt_pk_bf16_mfma(y[0], y[1]); w.y = cvt_pk_bf16(y[2], y[3]); *(u32x2*)yo = w; }
;                 else { const u32x2 p = pv[th][sx], u = uv[th][sx];
;                     const f32x2 v01 = (f32x2){y[0], y[1]} + (f32x2){bf_lo(p.x), bf_hi(p.x)} + dsk01 * (f32x2){bf_lo(u.x), bf_hi(u.x)};
;                     const f32x2 v23 = (f32x2){y[2], y[3]} + (f32x2){bf_lo(p.y), bf_hi(p.y)} + dsk23 * (f32x2){bf_lo(u.y), bf_hi(u.y)};
;                     const f32x2 o01 = gelu2(v01), o23 = gelu2(v23);
;                     u32x2 w; w.x = cvt_pk_bf16(o01.x, o01.y); w.y = cvt_pk_bf16(o23.x, o23.y); *(u32x2*)yo = w;
;                     { const unsigned x8 = pack_i8x4(o01.x, o01.y, o23.x, o23.y, 1.0f / YA8_R);
;                       *(unsigned*)(Y8 + (yo - YA)) = x8; }
;                     pv[th][sx] = *(const u32x2*)(yo + adv); uv[th][sx] = *(const u32x2*)(pU + th * CSTEP16 + sx * SSTEP + adv); }
	v_mfma_f32_16x16x32_bf16 v[0:3], v[100:103], v[16:19], v[0:3]
	s_nop 7
	v_pk_add_f32 v[0:1], v[0:1], v[22:23]
	v_lshlrev_b32_e32 v22, 16, v178
	v_and_b32_e32 v23, 0xffff0000, v178
	v_pk_fma_f32 v[22:23], v[64:65], v[22:23], v[0:1]
	v_lshlrev_b32_e32 v0, 16, v181
	v_and_b32_e32 v1, 0xffff0000, v181
	v_pk_add_f32 v[0:1], v[2:3], v[0:1]
	v_lshlrev_b32_e32 v2, 16, v179
	v_and_b32_e32 v3, 0xffff0000, v179
	v_pk_fma_f32 v[26:27], v[66:67], v[2:3], v[0:1]
	v_pk_mul_f32 v[0:1], v[22:23], v[22:23]
	v_mov_b64_e32 v[2:3], s[10:11]
	v_pk_fma_f32 v[0:1], v[0:1], s[0:1], v[2:3] op_sel_hi:[1,0,0] neg_lo:[1,0,0] neg_hi:[1,0,0]
	v_pk_mul_f32 v[28:29], v[26:27], v[26:27]
	v_pk_mul_f32 v[0:1], v[22:23], v[0:1]
	v_pk_fma_f32 v[28:29], v[28:29], s[0:1], v[2:3] op_sel_hi:[1,0,0] neg_lo:[1,0,0] neg_hi:[1,0,0]
	v_exp_f32_e32 v0, v0
	v_exp_f32_e32 v1, v1
	v_pk_mul_f32 v[28:29], v[26:27], v[28:29]
	s_mov_b64 s[10:11], 0x4c3ff800
	v_exp_f32_e32 v28, v28
	v_exp_f32_e32 v29, v29
	v_pk_add_f32 v[0:1], v[0:1], 1.0 op_sel_hi:[1,0]
	s_mov_b32 s1, 0x4c400000
	v_rcp_f32_e32 v30, v0
	v_rcp_f32_e32 v31, v1
	v_pk_add_f32 v[0:1], v[28:29], 1.0 op_sel_hi:[1,0]
	v_pk_mul_f32 v[22:23], v[22:23], v[30:31]
	v_rcp_f32_e32 v28, v0
	v_rcp_f32_e32 v29, v1
	v_lshl_add_u64 v[0:1], v[20:21], 0, s[10:11]
	v_add_co_u32_e32 v20, vcc, s1, v20
	v_pk_mul_f32 v[26:27], v[26:27], v[28:29]
	s_nop 0
	v_addc_co_u32_e32 v21, vcc, 0, v21, vcc
	v_cvt_pk_bf16_f32 v28, v22, v23
	v_cvt_pk_bf16_f32 v29, v26, v27
	global_store_dwordx2 v[20:21], v[28:29], off
	v_mul_f32_e32 v20, 0x3d924925, v22
	v_mul_f32_e32 v21, 0x3d924925, v23
	v_cvt_pknorm_i16_f32 v28, v20, v21
	v_mul_f32_e32 v20, 0x3d924925, v26
	v_mul_f32_e32 v21, 0x3d924925, v27
	v_cvt_pknorm_i16_f32 v26, v20, v21
	v_mfma_f32_16x16x32_bf16 v[20:23], v[84:87], v[144:147], 0
	s_movk_i32 s1, 0x80
	v_pk_add_i16 v27, v28, s1 op_sel_hi:[1,0] clamp
	v_pk_add_i16 v26, v26, s1 op_sel_hi:[1,0] clamp
	v_mfma_f32_16x16x32_bf16 v[4:7], v[68:71], v[4:7], v[20:23]
	s_mov_b32 s10, 0x7050301
	v_mfma_f32_16x16x32_bf16 v[4:7], v[72:75], v[8:11], v[4:7]
	s_nop 1
	v_mov_b32_e32 v21, s7
	v_subrev_co_u32_e32 v8, vcc, s6, v24
	v_mfma_f32_16x16x32_bf16 v[4:7], v[76:79], v[12:15], v[4:7]
	s_nop 0
	v_subb_co_u32_e32 v9, vcc, v25, v21, vcc
	v_ashrrev_i64 v[8:9], 1, v[8:9]
	v_mfma_f32_16x16x32_bf16 v[4:7], v[80:83], v[16:19], v[4:7]
	v_perm_b32 v20, v26, v27, s10
	v_bfe_u32 v9, v8, 4, 15
	v_lshlrev_b32_e32 v9, 6, v9
	v_bfi_b32 v8, s98, v9, v8
	v_lshrrev_b32_e32 v9, 15, v9
	v_bfi_b32 v8, 48, v9, v8
	global_store_dword v8, v20, s[8:9]
	v_lshlrev_b32_e32 v8, 16, v176
	v_and_b32_e32 v9, 0xffff0000, v176
	s_nop 2
	v_pk_add_f32 v[4:5], v[4:5], v[8:9]
	v_lshlrev_b32_e32 v8, 16, v172
	v_and_b32_e32 v9, 0xffff0000, v172
	v_pk_fma_f32 v[4:5], v[64:65], v[8:9], v[4:5]
	v_lshlrev_b32_e32 v8, 16, v177
	v_and_b32_e32 v9, 0xffff0000, v177
	v_pk_add_f32 v[6:7], v[6:7], v[8:9]
	v_lshlrev_b32_e32 v8, 16, v173
	v_and_b32_e32 v9, 0xffff0000, v173
	v_pk_fma_f32 v[6:7], v[66:67], v[8:9], v[6:7]
	v_pk_mul_f32 v[8:9], v[4:5], v[4:5]
	v_pk_mul_f32 v[10:11], v[6:7], v[6:7]
	v_pk_fma_f32 v[8:9], v[8:9], s[0:1], v[2:3] op_sel_hi:[1,0,0] neg_lo:[1,0,0] neg_hi:[1,0,0]
	v_pk_fma_f32 v[10:11], v[10:11], s[0:1], v[2:3] op_sel_hi:[1,0,0] neg_lo:[1,0,0] neg_hi:[1,0,0]
	v_pk_mul_f32 v[8:9], v[4:5], v[8:9]
	v_pk_mul_f32 v[10:11], v[6:7], v[10:11]
	v_exp_f32_e32 v8, v8
	v_exp_f32_e32 v9, v9
	v_exp_f32_e32 v10, v10
	v_exp_f32_e32 v11, v11
	s_waitcnt vmcnt(2)
	v_mfma_f32_16x16x32_bf16 v[12:15], v[104:107], v[140:143], 0
	v_add_f32_e64 v8, v8, 1.0
	v_add_f32_e64 v9, v9, 1.0
	v_lshl_add_u64 v[24:25], v[0:1], 0, s[12:13]
	v_rcp_f32_e32 v8, v8
	v_rcp_f32_e32 v9, v9
	v_pk_add_f32 v[10:11], v[10:11], 1.0 op_sel_hi:[1,0]
	v_mov_b32_e32 v27, s7
	v_rcp_f32_e32 v10, v10
	v_rcp_f32_e32 v11, v11
	v_pk_mul_f32 v[4:5], v[4:5], v[8:9]
	v_subrev_co_u32_e32 v24, vcc, s6, v24
	v_pk_mul_f32 v[6:7], v[6:7], v[10:11]
	v_cvt_pk_bf16_f32 v8, v4, v5
	v_mul_f32_e32 v4, 0x3d924925, v4
	v_mul_f32_e32 v5, 0x3d924925, v5
	v_cvt_pk_bf16_f32 v9, v6, v7
	global_store_dwordx2 v[0:1], v[8:9], off offset:2080
	v_cvt_pknorm_i16_f32 v16, v4, v5
	v_mul_f32_e32 v4, 0x3d924925, v6
	v_mul_f32_e32 v5, 0x3d924925, v7
	v_cvt_pknorm_i16_f32 v17, v4, v5
	ds_read_b128 v[4:7], v193 offset:4096
	ds_read_b128 v[8:11], v192 offset:4096
	s_waitcnt lgkmcnt(0)
	v_mfma_f32_16x16x32_bf16 v[12:15], v[88:91], v[8:11], v[12:15]
	v_pk_add_i16 v16, v16, s1 op_sel_hi:[1,0] clamp
	v_pk_add_i16 v17, v17, s1 op_sel_hi:[1,0] clamp
	v_subb_co_u32_e32 v25, vcc, v25, v27, vcc
	v_perm_b32 v26, v17, v16, s10
	ds_read_b128 v[16:19], v191 offset:4096
	ds_read_b128 v[20:23], v190 offset:4096
	v_mfma_f32_16x16x32_bf16 v[12:15], v[92:95], v[4:7], v[12:15]
	v_ashrrev_i64 v[24:25], 1, v[24:25]
	v_bfe_u32 v25, v24, 4, 15
	v_lshlrev_b32_e32 v25, 6, v25
	v_bfi_b32 v24, s98, v25, v24
	v_lshrrev_b32_e32 v25, 15, v25
	v_bfi_b32 v24, 48, v25, v24
	global_store_dword v24, v26, s[8:9]
	s_waitcnt lgkmcnt(0)
; __device__ __forceinline__ unsigned cvt_pk_bf16(float lo, float hi) { unsigned r; asm volatile("v_cvt_pk_bf16_f32 %0, %1, %2" : "=v"(r) : "v"(lo), "v"(hi)); return r; }
; __device__ __forceinline__ unsigned cvt_pk_bf16_mfma(float lo, float hi) { unsigned r; asm volatile("s_nop 7\n\ts_nop 4\n\tv_cvt_pk_bf16_f32 %0, %1, %2" : "=v"(r) : "v"(lo), "v"(hi)); return r; }
; __device__ __forceinline__ float bf_lo(unsigned w) { return __uint_as_float(w << 16); }
; __device__ __forceinline__ float bf_hi(unsigned w) { return __uint_as_float(w & 0xffff0000u); }
; template <bool REV> ...
;     ...
;                 f32x4 y = (f32x4){0.f, 0.f, 0.f, 0.f};
;                 y = __builtin_amdgcn_mfma_f32_16x16x32_bf16(Kf[sx], Ub[th], y, 0, 0, 0);
; #pragma unroll
;                 for (int ks = 0; ks < 4; ++ks) y = __builtin_amdgcn_mfma_f32_16x16x32_bf16(Cf[sx][ks], Hf[ks], y, 0, 0, 0);
;                 bf16* yo = pY + th * CSTEP16 + sx * SSTEP;
;                 if (!second) { u32x2 w; w.x = cvt_pk_bf16_mfma(y[0], y[1]); w.y = cvt_pk_bf16(y[2], y[3]); *(u32x2*)yo = w; }
;                 else { const u32x2 p = pv[th][sx], u = uv[th][sx];
;                     const f32x2 v01 = (f32x2){y[0], y[1]} + (f32x2){bf_lo(p.x), bf_hi(p.x)} + dsk01 * (f32x2){bf_lo(u.x), bf_hi(u.x)};
;                     const f32x2 v23 = (f32x2){y[2], y[3]} + (f32x2){bf_lo(p.y), bf_hi(p.y)} + dsk23 * (f32x2){bf_lo(u.y), bf_hi(u.y)};
;                     const f32x2 o01 = gelu2(v01), o23 = gelu2(v23);
;                     u32x2 w; w.x = cvt_pk_bf16(o01.x, o01.y); w.y = cvt_pk_bf16(o23.x, o23.y); *(u32x2*)yo = w;
;                     { const unsigned x8 = pack_i8x4(o01.x, o01.y, o23.x, o23.y, 1.0f / YA8_R);
;                       *(unsigned*)(Y8 + (yo - YA)) = x8; }
;                     pv[th][sx] = *(const u32x2*)(yo + adv); uv[th][sx] = *(const u32x2*)(pU + th * CSTEP16 + sx * SSTEP + adv); }
	v_mfma_f32_16x16x32_bf16 v[12:15], v[96:99], v[20:23], v[12:15]
	v_lshlrev_b32_e32 v24, 16, v170
	v_and_b32_e32 v25, 0xffff0000, v170
	s_mov_b64 s[12:13], 0xc00
	v_mfma_f32_16x16x32_bf16 v[12:15], v[100:103], v[16:19], v[12:15]
	v_lshl_add_u64 v[28:29], v[0:1], 0, s[12:13]
	s_nop 6
	v_pk_add_f32 v[12:13], v[12:13], v[24:25]
	v_lshlrev_b32_e32 v24, 16, v168
	v_and_b32_e32 v25, 0xffff0000, v168
	v_pk_fma_f32 v[12:13], v[64:65], v[24:25], v[12:13]
	v_lshlrev_b32_e32 v24, 16, v171
	v_and_b32_e32 v25, 0xffff0000, v171
	v_pk_add_f32 v[14:15], v[14:15], v[24:25]
	v_lshlrev_b32_e32 v24, 16, v169
	v_and_b32_e32 v25, 0xffff0000, v169
	v_pk_fma_f32 v[14:15], v[66:67], v[24:25], v[14:15]
	v_pk_mul_f32 v[24:25], v[12:13], v[12:13]
	v_pk_mul_f32 v[26:27], v[14:15], v[14:15]
	v_pk_fma_f32 v[24:25], v[24:25], s[0:1], v[2:3] op_sel_hi:[1,0,0] neg_lo:[1,0,0] neg_hi:[1,0,0]
	v_pk_fma_f32 v[26:27], v[26:27], s[0:1], v[2:3] op_sel_hi:[1,0,0] neg_lo:[1,0,0] neg_hi:[1,0,0]
	v_pk_mul_f32 v[24:25], v[12:13], v[24:25]
	v_pk_mul_f32 v[26:27], v[14:15], v[26:27]
	v_exp_f32_e32 v24, v24
	v_exp_f32_e32 v25, v25
	v_exp_f32_e32 v26, v26
	v_exp_f32_e32 v27, v27
	v_pk_add_f32 v[24:25], v[24:25], 1.0 op_sel_hi:[1,0]
	s_nop 0
	v_rcp_f32_e32 v24, v24
	v_rcp_f32_e32 v25, v25
	v_pk_add_f32 v[26:27], v[26:27], 1.0 op_sel_hi:[1,0]
	v_pk_mul_f32 v[12:13], v[12:13], v[24:25]
	v_rcp_f32_e32 v26, v26
	v_rcp_f32_e32 v27, v27
	s_nop 0
	v_pk_mul_f32 v[24:25], v[14:15], v[26:27]
	v_cvt_pk_bf16_f32 v14, v12, v13
	s_nop 0
	v_cvt_pk_bf16_f32 v15, v24, v25
	v_mul_f32_e32 v12, 0x3d924925, v12
	v_mul_f32_e32 v13, 0x3d924925, v13
	global_store_dwordx2 v[0:1], v[14:15], off offset:3072
	v_cvt_pknorm_i16_f32 v26, v12, v13
	v_mfma_f32_16x16x32_bf16 v[12:15], v[84:87], v[140:143], 0
	v_mul_f32_e32 v24, 0x3d924925, v24
	v_mul_f32_e32 v25, 0x3d924925, v25
	v_cvt_pknorm_i16_f32 v24, v24, v25
	v_mfma_f32_16x16x32_bf16 v[8:11], v[68:71], v[8:11], v[12:15]
	v_pk_add_i16 v25, v26, s1 op_sel_hi:[1,0] clamp
	v_mfma_f32_16x16x32_bf16 v[4:7], v[72:75], v[4:7], v[8:11]
	s_nop 1
	v_mov_b32_e32 v13, s7
	v_pk_add_i16 v12, v24, s1 op_sel_hi:[1,0] clamp
	v_mfma_f32_16x16x32_bf16 v[4:7], v[76:79], v[20:23], v[4:7]
	s_nop 0
	v_subrev_co_u32_e32 v8, vcc, s6, v28
	v_perm_b32 v12, v12, v25, s10
	s_nop 0
	v_subb_co_u32_e32 v9, vcc, v29, v13, vcc
	v_mfma_f32_16x16x32_bf16 v[4:7], v[80:83], v[16:19], v[4:7]
	v_ashrrev_i64 v[8:9], 1, v[8:9]
	v_bfe_u32 v9, v8, 4, 15
	v_lshlrev_b32_e32 v9, 6, v9
	v_bfi_b32 v8, s98, v9, v8
	v_lshrrev_b32_e32 v9, 15, v9
	v_bfi_b32 v8, 48, v9, v8
	global_store_dword v8, v12, s[8:9]
	v_lshlrev_b32_e32 v8, 16, v162
	v_and_b32_e32 v9, 0xffff0000, v162
	s_nop 2
	v_pk_add_f32 v[4:5], v[4:5], v[8:9]
	v_lshlrev_b32_e32 v8, 16, v166
	v_and_b32_e32 v9, 0xffff0000, v166
	v_pk_fma_f32 v[4:5], v[64:65], v[8:9], v[4:5]
	v_lshlrev_b32_e32 v8, 16, v163
	v_and_b32_e32 v9, 0xffff0000, v163
	v_pk_add_f32 v[6:7], v[6:7], v[8:9]
	v_lshlrev_b32_e32 v8, 16, v167
	v_and_b32_e32 v9, 0xffff0000, v167
	v_pk_fma_f32 v[6:7], v[66:67], v[8:9], v[6:7]
	v_pk_mul_f32 v[8:9], v[4:5], v[4:5]
	v_pk_mul_f32 v[10:11], v[6:7], v[6:7]
	v_pk_fma_f32 v[8:9], v[8:9], s[0:1], v[2:3] op_sel_hi:[1,0,0] neg_lo:[1,0,0] neg_hi:[1,0,0]
	v_pk_fma_f32 v[2:3], v[10:11], s[0:1], v[2:3] op_sel_hi:[1,0,0] neg_lo:[1,0,0] neg_hi:[1,0,0]
	v_pk_mul_f32 v[8:9], v[4:5], v[8:9]
	v_pk_mul_f32 v[2:3], v[6:7], v[2:3]
	v_exp_f32_e32 v8, v8
	v_exp_f32_e32 v9, v9
	v_exp_f32_e32 v2, v2
	v_exp_f32_e32 v3, v3
	s_mov_b64 s[0:1], 0xc20
	v_pk_add_f32 v[8:9], v[8:9], 1.0 op_sel_hi:[1,0]
	v_pk_add_f32 v[2:3], v[2:3], 1.0 op_sel_hi:[1,0]
	v_rcp_f32_e32 v8, v8
	v_rcp_f32_e32 v9, v9
	v_rcp_f32_e32 v10, v2
	v_rcp_f32_e32 v11, v3
	v_lshl_add_u64 v[2:3], v[0:1], 0, s[0:1]
	v_pk_mul_f32 v[4:5], v[4:5], v[8:9]
	v_pk_mul_f32 v[6:7], v[6:7], v[10:11]
	v_cvt_pk_bf16_f32 v8, v4, v5
	s_nop 0
	v_cvt_pk_bf16_f32 v9, v6, v7
	global_store_dwordx2 v[0:1], v[8:9], off offset:3104
.LBB0_422:
	v_mul_f32_e32 v0, 0x3d924925, v4
	v_mul_f32_e32 v1, 0x3d924925, v5
	v_cvt_pknorm_i16_f32 v0, v0, v1
	v_mul_f32_e32 v1, 0x3d924925, v6
	v_mul_f32_e32 v4, 0x3d924925, v7
	v_cvt_pknorm_i16_f32 v1, v1, v4
	s_movk_i32 s0, 0x80
	v_pk_add_i16 v0, v0, s0 op_sel_hi:[1,0] clamp
	v_pk_add_i16 v1, v1, s0 op_sel_hi:[1,0] clamp
	s_mov_b32 s0, 0x7050301
	v_perm_b32 v4, v1, v0, s0
	v_mov_b32_e32 v1, s7
	v_subrev_co_u32_e32 v0, vcc, s6, v2
	s_nop 1
	v_subb_co_u32_e32 v1, vcc, v3, v1, vcc
	v_ashrrev_i64 v[0:1], 1, v[0:1]
	v_bfe_u32 v1, v0, 4, 15
	v_lshlrev_b32_e32 v1, 6, v1
	v_bfi_b32 v0, s98, v1, v0
	v_lshrrev_b32_e32 v1, 15, v1
	v_bfi_b32 v0, 48, v1, v0
	global_store_dword v0, v4, s[8:9]

; __device__ __forceinline__ int lane_id_asm() { int l; asm volatile("v_mbcnt_lo_u32_b32 %0, -1, 0\n\tv_mbcnt_hi_u32_b32 %0, -1, %0" : "=v"(l)); return l; }
; #define PG8_WAIT_V(n) asm volatile("s_waitcnt vmcnt(" #n ")" ::: "memory")
; template <class Epi, class Sched>
; __device__ __forceinline__ void gemm_phase(PG8_LAS unsigned char* lds, const Gemm g, const Sched& S, const Epi& E, int wave_) {
;     const int wid = wave_, lane = lane_id_asm(), tid = wid * 64 + lane, wr = wid >> 2, wc = wid & 3, fr = lane & 15, fq = lane >> 4;
;     const int K = g.K, nt = K / BK;
;     unsigned voffA[2], voffB[2];
; #pragma unroll
;     for (int i = 0; i < 2; ++i) { int R, C; stage_rc(tid * 16 + i * 8192, R, C); const int Rb = Epi::PERM ? ((R & ~31) + perm32(R & 31)) : R;
;         voffA[i] = g.a_gm == 2 ? (unsigned)(((C >> 3) * SEQ + R) * 16) : g.a_gm ? (unsigned)(((C >> 4) * SEQ + R) * 32 + (C & 15) * 2) : (unsigned)(R * g.lda + C) * 2u; voffB[i] = (unsigned)(Rb * g.ldb + C) * 2u; }
;     const int gmb = g.a_gm == 2 ? 16 : 32;
;     const size_t kstep = (size_t)(BK * 2), kstepA = g.a_gm ? (size_t)(128 / gmb) * SEQ * gmb : kstep;
;     const size_t hsA = g.a_gm ? (size_t)HALF * gmb : (size_t)HALF * g.lda * 2, hsB = (size_t)HALF * g.ldb * 2;
;     ...
;     const unsigned ldsw = (unsigned)wid * 1024u;
;     const int aoff = lds_byte(wr * 64 + fr, fq * 8), boff = lds_byte(wc * 32 + fr, fq * 8);
;     ...
;     Unit cur, nxt; int ui = 0;
;     if (!S.next(0, cur)) return;
;     f32x4 acc[2][2][4][2];
; #pragma unroll
;     for (int a = 0; a < 2; ++a)
; #pragma unroll
;         for (int b = 0; b < 2; ++b)
; #pragma unroll
;             for (int m = 0; m < 4; ++m)
; #pragma unroll
;                 for (int n = 0; n < 2; ++n) acc[a][b][m][n] = (f32x4){0.f, 0.f, 0.f, 0.f};
;     i32x8 At[4], B0[2], B1[2];
;     const char* cA = PG8_PANEL_A(cur); const char* cB = (const char*)(g.Bt + (size_t)cur.grp * g.b_gs) + (size_t)cur.pn * 2 * hsB;
;     PG8_STAGE(PG8_SB(0, 0), cB, voffB); PG8_STAGE(PG8_SB(0, 1), cB + hsB, voffB); PG8_STAGE(PG8_SA(0, 0), cA, voffA); PG8_STAGE(PG8_SA(0, 1), cA + hsA, voffA);
;     if (wr == 1) PG8_BAR;
;     PG8_WAIT_V(2); PG8_BAR;
;     PG8_STAGE(PG8_SB(1, 0), cB + kstep, voffB); PG8_STAGE(PG8_SA(1, 0), cA + kstepA, voffA); PG8_STAGE(PG8_SB(1, 1), cB + hsB + kstep, voffB); PG8_STAGE(PG8_SA(1, 1), cA + kstepA + hsA, voffA);
;     PG8_WAIT_V(0); PG8_BAR;
.LBB0_477:
	s_cmp_lt_i32 s14, 5
	s_cselect_b64 s[4:5], -1, 0
	s_and_b64 s[0:1], s[4:5], s[0:1]
	s_andn2_b64 vcc, exec, s[0:1]
	s_cbranch_vccnz .LBB0_506
	s_cmpk_gt_i32 s2, 0x7ff
	v_mbcnt_lo_u32_b32 v0, -1, 0
	v_mbcnt_hi_u32_b32 v0, -1, v0
	v_mbcnt_lo_u32_b32 v4, -1, 0
	v_mbcnt_hi_u32_b32 v4, -1, v4
	s_cbranch_scc1 .LBB0_506
	s_add_u32 s6, s30, 0x70400000
	s_addc_u32 s7, s31, 0
	s_add_u32 s33, s30, 0x11800000
	v_readlane_b32 s4, v252, 0
	s_addc_u32 s34, s31, 0
	s_lshr_b32 s18, s4, 8
	s_ashr_i32 s4, s2, 8
	s_lshr_b32 s5, s2, 31
	s_add_i32 s5, s4, s5
	s_and_b32 s9, s5, -2
	s_ashr_i32 s8, s5, 1
	s_sub_i32 s4, s4, s9
	s_lshl_b32 s10, s95, 10
	s_and_b32 s9, s8, 1
	s_sub_i32 s11, 1, s4
	s_cmp_eq_u32 s9, 0
	s_cselect_b32 s4, s4, s11
	s_lshl_b32 s9, s2, 3
	v_lshl_add_u32 v0, v4, 4, s10
	s_and_b32 s9, s9, 8
	s_bfe_u32 s11, s2, 0x30003
	v_add_u32_e32 v1, 0x2000, v0
	s_lshl_b32 s8, s8, 4
	s_or_b32 s9, s9, s11
	v_ashrrev_i32_e32 v2, 31, v1
	s_or_b32 s86, s9, s8
	s_lshl_b32 s8, s2, 1
	v_lshrrev_b32_e32 v2, 22, v2
	s_lshl_b32 s4, s4, 4
	s_and_b32 s8, s8, 12
	v_add_u32_e32 v2, v1, v2
	s_or_b32 s4, s4, s8
	s_bfe_u32 s8, s2, 0x20006
	v_ashrrev_i32_e32 v2, 10, v2
	s_waitcnt lgkmcnt(0)
	s_or_b32 s52, s4, s8
	s_ashr_i32 s4, s5, 2
	v_mul_i32_i24_e32 v3, 0x400, v2
	s_ashr_i32 s5, s4, 31
	v_sub_u32_e32 v1, v1, v3
	s_lshl_b32 s8, s86, 14
	s_lshl_b64 s[4:5], s[4:5], 26
	v_lshrrev_b32_e32 v3, 4, v1
	s_add_u32 s9, s6, s4
	v_bitop3_b32 v1, v3, v1, 32 bitop3:0x6c
	s_addc_u32 s11, s7, s5
	s_ashr_i32 s53, s52, 31
	v_ashrrev_i32_e32 v3, 31, v1
	s_lshl_b64 s[4:5], s[52:53], 21
	v_lshrrev_b32_e32 v3, 26, v3
	s_add_u32 s56, s33, s4
	v_add_u32_e32 v3, v1, v3
	s_addc_u32 s57, s34, s5
	s_and_b32 s4, s8, 0x7c000
	v_ashrrev_i32_e32 v5, 6, v3
	v_and_b32_e32 v3, 0xffc0, v3
	s_add_u32 s54, s9, s4
	v_sub_u32_e32 v1, v1, v3
	s_addc_u32 s55, s11, 0
	v_lshlrev_b32_e32 v6, 3, v2
	v_lshrrev_b16_e32 v3, 7, v1
	s_cmp_eq_u32 s18, 1
	v_and_b32_e32 v6, -16, v6
	v_and_b32_e32 v3, 1, v3
	s_cselect_b64 s[4:5], -1, 0
	s_add_u32 s8, s56, 0x100000
	v_add_u32_e32 v8, v5, v6
	v_lshlrev_b32_e32 v2, 5, v2
	v_add_u16_e32 v1, v1, v3
	v_mov_b32_e32 v3, 1
	s_addc_u32 s9, s57, 0
	s_add_i32 s35, s10, 0
	v_and_b32_e32 v7, 3, v5
	s_mov_b32 s10, 0x7ffe0
	v_lshrrev_b32_e32 v9, 2, v8
	v_lshlrev_b32_e32 v10, 1, v8
	v_and_b32_e32 v2, 32, v2
	v_ashrrev_i16_sdwa v1, v3, sext(v1) dst_sel:DWORD dst_unused:UNUSED_PAD src0_sel:DWORD src1_sel:BYTE_0
	v_and_or_b32 v7, v8, s10, v7
	v_and_b32_e32 v9, 4, v9
	v_and_b32_e32 v10, 24, v10
	v_add_u32_sdwa v1, v2, sext(v1) dst_sel:DWORD dst_unused:UNUSED_PAD src0_sel:DWORD src1_sel:WORD_0
	v_or3_b32 v7, v7, v9, v10
	v_lshlrev_b32_e32 v2, 1, v1
	v_lshlrev_b32_e32 v1, 10, v1
	v_lshl_add_u32 v192, v7, 13, v2
	v_lshrrev_b32_e32 v7, 9, v1
	v_and_b32_e32 v7, 48, v7
	v_lshlrev_b32_e32 v1, 4, v1
	v_and_b32_e32 v1, 0x80000, v1
	v_or_b32_e32 v7, v7, v1
	v_ashrrev_i32_e32 v1, 31, v0
	v_lshrrev_b32_e32 v1, 22, v1
	v_add_u32_e32 v1, v0, v1
	v_ashrrev_i32_e32 v1, 10, v1
	v_mul_i32_i24_e32 v2, 0x400, v1
	v_sub_u32_e32 v0, v0, v2
	v_lshrrev_b32_e32 v2, 4, v0
	v_bitop3_b32 v0, v2, v0, 32 bitop3:0x6c
	v_ashrrev_i32_e32 v2, 31, v0
	v_lshrrev_b32_e32 v2, 26, v2
	v_add_u32_e32 v2, v0, v2
	v_lshlrev_b32_e32 v9, 3, v1
	v_lshl_add_u32 v194, v8, 6, v7
	v_ashrrev_i32_e32 v8, 6, v2
	v_and_b32_e32 v9, -16, v9
	v_and_b32_e32 v2, 0xc0, v2
	v_add_u32_e32 v11, v8, v9
	v_lshlrev_b32_e32 v1, 5, v1
	v_sub_u32_e32 v0, v0, v2
	v_and_b32_e32 v10, 3, v8
	v_lshrrev_b32_e32 v12, 2, v11
	v_lshlrev_b32_e32 v13, 1, v11
	v_and_b32_e32 v1, 32, v1
	v_ashrrev_i16_sdwa v0, v3, sext(v0) dst_sel:DWORD dst_unused:UNUSED_PAD src0_sel:DWORD src1_sel:BYTE_0
	v_and_or_b32 v10, v11, s10, v10
	v_and_b32_e32 v12, 4, v12
	v_and_b32_e32 v13, 24, v13
	v_add_u32_sdwa v0, v1, sext(v0) dst_sel:DWORD dst_unused:UNUSED_PAD src0_sel:DWORD src1_sel:WORD_0
	s_add_i32 s53, s35, 0x10000
	v_or3_b32 v10, v10, v12, v13
	v_lshlrev_b32_e32 v1, 1, v0
	s_add_i32 s66, s35, 0x12000
	v_lshl_add_u32 v196, v10, 13, v1
	s_mov_b32 m0, s53
	s_add_i32 s67, s35, 0x14000
	global_load_lds_dwordx4 v196, s[56:57]
	s_mov_b32 m0, s66
	s_add_i32 s68, s35, 0x16000
	v_lshlrev_b32_e32 v0, 10, v0
	global_load_lds_dwordx4 v192, s[56:57]
	s_mov_b32 m0, s67
	v_lshrrev_b32_e32 v10, 9, v0
	v_and_b32_e32 v10, 48, v10
	v_lshlrev_b32_e32 v0, 4, v0
	v_and_b32_e32 v0, 0x80000, v0
	v_or_b32_e32 v10, v10, v0
	v_mov_b32_e32 v201, 0
	global_load_lds_dwordx4 v196, s[8:9]
	s_mov_b32 m0, s68
	s_add_i32 s69, s35, 0x2000
	v_lshl_add_u32 v198, v11, 6, v10
	global_load_lds_dwordx4 v192, s[8:9]
	v_mov_b32_e32 v199, v201
	s_mov_b32 m0, s35
	s_add_i32 s72, s35, 0x4000
	v_lshl_add_u64 v[0:1], s[54:55], 0, v[198:199]
	global_load_lds_dwordx4 v198, s[54:55]
	v_mov_b32_e32 v195, v201
	s_mov_b32 m0, s69
	s_mov_b64 s[8:9], 0x2000
	s_add_i32 s73, s35, 0x6000
	v_lshl_add_u64 v[2:3], s[54:55], 0, v[194:195]
	global_load_lds_dwordx4 v194, s[54:55]
	v_lshl_add_u64 v[0:1], v[0:1], 0, s[8:9]
	s_mov_b32 m0, s72
	v_mov_b32_e32 v197, v201
	global_load_lds_dwordx4 v[0:1], off
	v_lshl_add_u64 v[0:1], v[2:3], 0, s[8:9]
	s_mov_b32 m0, s73
	v_mov_b32_e32 v193, v201
	global_load_lds_dwordx4 v[0:1], off
	s_mov_b32 s74, 0
	s_cmp_lg_u32 s18, 1
	v_lshl_add_u64 v[2:3], s[56:57], 0, v[196:197]
	v_lshl_add_u64 v[0:1], s[56:57], 0, v[192:193]
	s_cbranch_scc1 .LBB0_481
	s_barrier
;     __device__ __forceinline__ bool next(int i, Unit& u) const { const int L = i * G + c; if (L >= nM * nN) return false; static_unit(L, nM, nN, u.pm, u.pn); u.grp = 0; return true; }
;     __device__ __forceinline__ bool next(int i, Unit& u) const { const int L = i * G + c; if (L >= 256) return false; const int cu = L >> 2; u.grp = L & 3; u.pm = 64 + (cu >> 5); u.pn = cu & 31; return true; }
;     __device__ __forceinline__ bool next(int i, Unit& u) const { const int L = i * G + c; if (L >= 2048) return false; u.grp = L >> 9; static_unit(L & 511, 64, 8, u.pm, u.pn); return true; }
; template <class Epi, class Sched>
; __device__ __forceinline__ void gemm_phase(PG8_LAS unsigned char* lds, const Gemm g, const Sched& S, const Epi& E, int wave_) {
;     ...
;         voffA[i] = g.a_gm == 2 ? (unsigned)(((C >> 3) * SEQ + R) * 16) : g.a_gm ? (unsigned)(((C >> 4) * SEQ + R) * 32 + (C & 15) * 2) : (unsigned)(R * g.lda + C) * 2u; voffB[i] = (unsigned)(Rb * g.ldb + C) * 2u; }
;     const int gmb = g.a_gm == 2 ? 16 : 32;
;     const size_t kstep = (size_t)(BK * 2), kstepA = g.a_gm ? (size_t)(128 / gmb) * SEQ * gmb : kstep;
;     const size_t hsA = g.a_gm ? (size_t)HALF * gmb : (size_t)HALF * g.lda * 2, hsB = (size_t)HALF * g.ldb * 2;
;     ...
;     const unsigned ldsw = (unsigned)wid * 1024u;
;     const int aoff = lds_byte(wr * 64 + fr, fq * 8), boff = lds_byte(wc * 32 + fr, fq * 8);
;     ...
;     Unit cur, nxt; int ui = 0;
;     if (!S.next(0, cur)) return;
;     f32x4 acc[2][2][4][2];
; #pragma unroll
;     for (int a = 0; a < 2; ++a)
; #pragma unroll
;         for (int b = 0; b < 2; ++b)
; #pragma unroll
;             for (int m = 0; m < 4; ++m)
; #pragma unroll
;                 for (int n = 0; n < 2; ++n) acc[a][b][m][n] = (f32x4){0.f, 0.f, 0.f, 0.f};
;     i32x8 At[4], B0[2], B1[2];
;     const char* cA = PG8_PANEL_A(cur); const char* cB = (const char*)(g.Bt + (size_t)cur.grp * g.b_gs) + (size_t)cur.pn * 2 * hsB;
;     PG8_STAGE(PG8_SB(0, 0), cB, voffB); PG8_STAGE(PG8_SB(0, 1), cB + hsB, voffB); PG8_STAGE(PG8_SA(0, 0), cA, voffA); PG8_STAGE(PG8_SA(0, 1), cA + hsA, voffA);
;     if (wr == 1) PG8_BAR;
;     PG8_WAIT_V(2); PG8_BAR;
;     PG8_STAGE(PG8_SB(1, 0), cB + kstep, voffB); PG8_STAGE(PG8_SA(1, 0), cA + kstepA, voffA); PG8_STAGE(PG8_SB(1, 1), cB + hsB + kstep, voffB); PG8_STAGE(PG8_SA(1, 1), cA + kstepA + hsA, voffA);
;     PG8_WAIT_V(0); PG8_BAR;
.LBB0_481:
	s_add_u32 s10, s30, 0x4c400000
	s_addc_u32 s11, s31, 0
	s_add_u32 s12, s30, 0x3c400000
	s_addc_u32 s13, s31, 0
	s_add_u32 s16, s30, 0x2bc00000
	s_addc_u32 s17, s31, 0
	s_lshl_b32 s75, s18, 6
	s_lshl_b32 s50, s18, 13
	s_lshl_b32 s18, s95, 5
	s_and_b32 s51, s18, 0x60
	s_lshr_b32 s58, s51, 3
	s_add_u32 s40, s54, 0x100000
	s_addc_u32 s41, s55, 0
	s_add_u32 s42, s56, 0x100080
	s_addc_u32 s43, s57, 0
	s_add_u32 s46, s54, 0x102000
	s_addc_u32 s47, s55, 0
	v_readlane_b32 s18, v252, 0
	s_cmpk_lt_u32 s18, 0x100
	s_cselect_b64 s[18:19], -1, 0
	s_add_u32 s22, s30, 0x1780004
	s_addc_u32 s23, s31, 0
	s_mov_b64 s[38:39], 0x80
	s_add_i32 s76, s35, 0x18000
	v_lshl_add_u64 v[2:3], v[2:3], 0, s[38:39]
	s_mov_b32 m0, s76
	s_add_i32 s77, s35, 0x1a000
	s_waitcnt vmcnt(2)
	s_barrier
	global_load_lds_dwordx4 v[2:3], off
	v_lshl_add_u64 v[0:1], v[0:1], 0, s[38:39]
	s_mov_b32 m0, s77
	s_add_i32 s78, s35, 0x8000
	global_load_lds_dwordx4 v[0:1], off
	v_lshl_add_u64 v[0:1], s[40:41], 0, v[198:199]
	s_mov_b32 m0, s78
	s_add_i32 s79, s35, 0xa000
	global_load_lds_dwordx4 v[0:1], off
	v_lshl_add_u64 v[0:1], s[40:41], 0, v[194:195]
	s_mov_b32 m0, s79
	s_add_i32 s80, s35, 0x1c000
	global_load_lds_dwordx4 v[0:1], off
	v_lshl_add_u64 v[0:1], s[42:43], 0, v[196:197]
	s_mov_b32 m0, s80
	s_add_i32 s81, s35, 0x1e000
	global_load_lds_dwordx4 v[0:1], off
	v_lshl_add_u64 v[0:1], s[42:43], 0, v[192:193]
	s_mov_b32 m0, s81
	s_add_i32 s82, s35, 0xc000
	global_load_lds_dwordx4 v[0:1], off
	v_lshl_add_u64 v[0:1], s[46:47], 0, v[198:199]
	s_mov_b32 m0, s82
	s_add_i32 s83, s35, 0xe000
	global_load_lds_dwordx4 v[0:1], off
	v_lshl_add_u64 v[0:1], s[46:47], 0, v[194:195]
	s_mov_b32 m0, s83
	v_and_b32_e32 v220, 15, v4
	global_load_lds_dwordx4 v[0:1], off
	v_ashrrev_i32_e32 v0, 1, v4
	v_and_b32_e32 v1, -8, v0
	v_ashrrev_i32_e32 v2, 6, v4
	v_and_b32_e32 v3, 48, v4
	v_lshlrev_b32_e32 v4, 2, v4
	v_lshl_or_b32 v3, v220, 6, v3
	v_and_b32_e32 v4, 32, v4
	v_add_u32_e32 v225, s51, v1
	v_add_u32_e32 v1, v8, v10
	s_mov_b64 s[40:41], 0x102000
	v_add_u32_e32 v11, s58, v2
	s_waitcnt vmcnt(0)
	v_xad_u32 v3, v3, v4, 0
	v_mov_b32_e32 v200, v198
	v_add_u32_e32 v1, v5, v7
	v_lshl_add_u32 v4, v11, 10, v3
	v_lshl_add_u32 v2, v2, 10, v3
	v_and_b32_e32 v0, 8, v0
	v_lshl_add_u64 v[202:203], v[200:201], 0, s[40:41]
	v_mov_b32_e32 v200, v194
	v_add_u32_e32 v221, 0x10000, v4
	v_add_u32_e32 v222, 0x14000, v4
	v_add_u32_e32 v223, 0x18000, v4
	v_add_u32_e32 v224, 0x1c000, v4
	v_add_u32_e32 v226, 0x10400, v4
	v_add_u32_e32 v227, 0x10800, v4
	v_add_u32_e32 v228, 0x10c00, v4
	v_add_u32_e32 v229, 0x14400, v4
	v_add_u32_e32 v230, 0x14800, v4
	v_add_u32_e32 v231, 0x14c00, v4
	v_add_u32_e32 v232, 0x18400, v4
	v_add_u32_e32 v233, 0x18800, v4
	v_add_u32_e32 v234, 0x18c00, v4
	v_add_u32_e32 v235, 0x1c400, v4
	v_add_u32_e32 v236, 0x1c800, v4
	v_add_u32_e32 v237, 0x1cc00, v4
	v_lshl_add_u64 v[204:205], v[200:201], 0, s[40:41]
	v_add_u32_e32 v238, s50, v2
	v_lshlrev_b32_e32 v206, 1, v0
	s_mov_b32 s84, 0x200000
	s_barrier
	s_branch .LBB0_484

; #define PG8_WAIT_V(n) asm volatile("s_waitcnt vmcnt(" #n ")" ::: "memory")
; #define PG8_BAR __builtin_amdgcn_s_barrier()
; template <class Epi, class Sched>
; __device__ __forceinline__ void gemm_phase(PG8_LAS unsigned char* lds, const Gemm g, const Sched& S, const Epi& E, int wave_) {
;     ...
;         const bool has_next = S.next(ui + 1, nxt);
;         const char* nA = has_next ? PG8_PANEL_A(nxt) : cA; const char* nB = has_next ? (const char*)(g.Bt + (size_t)nxt.grp * g.b_gs) + (size_t)nxt.pn * 2 * hsB : cB;
;     ...
; #pragma clang loop unroll(disable)
;         for (int t = 0; t < nt; t += 2) {
;             const bool last = (t == nt - 2);
;             const char* a1 = cA + (size_t)(t + 1) * kstepA;
;             const char* a2 = last ? nA : cA + (size_t)(t + 2) * kstepA; const char* b2 = last ? nB : cB + (size_t)(t + 2) * kstep;
;             const char* a3 = a2 + kstepA; const char* b3 = b2 + kstep;
;             PG8_LDB(B0, 0, 0); PG8_LDB(B1, 0, 1); PG8_SCHED; PG8_LDA(At, 0, 0); if (t != 0) PG8_STAGE(PG8_SA(1, 1), a1 + hsA, voffA);
;             PG8_WAIT_V0; PG8_WAIT_L(0); PG8_BAR; PG8_MMA(0, 0, At, B0); PG8_MMA(0, 1, At, B1); PG8_BAR; PG8_SCHED;
;             PG8_LDA(At, 0, 1); PG8_STAGE(PG8_SB(0, 0), b2, voffB); PG8_STAGE(PG8_SB(0, 1), b2 + hsB, voffB); PG8_STAGE(PG8_SA(0, 0), a2, voffA);
;             PG8_WAIT_V0; PG8_WAIT_L(0); PG8_BAR; PG8_MMA(1, 0, At, B0); PG8_MMA(1, 1, At, B1); PG8_BAR; PG8_SCHED;
;             PG8_LDB(B0, 1, 0); PG8_LDB(B1, 1, 1); PG8_SCHED; PG8_LDA(At, 1, 0); PG8_STAGE(PG8_SA(0, 1), a2 + hsA, voffA);
;             PG8_WAIT_V0; PG8_WAIT_L(0); PG8_BAR; PG8_MMA(0, 0, At, B0); PG8_MMA(0, 1, At, B1); PG8_BAR; PG8_SCHED;
;             PG8_LDA(At, 1, 1); PG8_STAGE(PG8_SB(1, 0), b3, voffB); PG8_STAGE(PG8_SB(1, 1), b3 + hsB, voffB); PG8_STAGE(PG8_SA(1, 0), a3, voffA);
;             PG8_WAIT_V(8); PG8_WAIT_L(0); PG8_BAR; PG8_MMA(1, 0, At, B0); PG8_MMA(1, 1, At, B1); PG8_BAR; PG8_SCHED;
;         }
;         PG8_STAGE(PG8_SA(1, 1), nA + kstepA + hsA, voffA);
;         if (wr == 0) PG8_BAR;
;         E(acc, cur, wr, wc, fr, fq);
;         if (!has_next) break;
; #pragma unroll
;         for (int a = 0; a < 2; ++a)
; #pragma unroll
;             for (int b = 0; b < 2; ++b)
; #pragma unroll
;                 for (int m = 0; m < 4; ++m)
; #pragma unroll
;                     for (int n = 0; n < 2; ++n) acc[a][b][m][n] = (f32x4){0.f, 0.f, 0.f, 0.f};
.LBB0_486:
	s_ashr_i32 s46, s85, 5
	s_ashr_i32 s47, s46, 31
	s_lshl_b32 s41, s85, 14
	s_and_b32 s41, s41, 0x7c000
	s_lshl_b64 s[46:47], s[46:47], 26
	s_add_u32 s46, s6, s46
	s_addc_u32 s47, s7, s47
	s_add_u32 s46, s46, s41
	s_addc_u32 s47, s47, 0
	s_and_b64 s[50:51], s[42:43], exec
	s_cselect_b32 s87, s47, s55
	s_cselect_b32 s88, s46, s54
	s_ashr_i32 s41, s40, 31
	s_lshl_b64 s[50:51], s[40:41], 21
	s_add_u32 s50, s33, s50
	s_addc_u32 s51, s34, s51
	s_and_b64 s[58:59], s[42:43], exec
	s_cselect_b32 s41, s51, s57
	s_cselect_b32 s89, s50, s56
	s_add_u32 s90, s56, 0x100
	v_mov_b32_e32 v0, 0
	s_addc_u32 s91, s57, 0
	v_lshl_add_u64 v[208:209], s[54:55], 0, v[202:203]
	v_lshl_add_u64 v[210:211], s[54:55], 0, v[204:205]
	s_mov_b32 s92, -2
	s_mov_b64 s[56:57], 0
	v_mov_b32_e32 v1, v0
	v_mov_b32_e32 v2, v0
	v_mov_b32_e32 v3, v0
	v_mov_b32_e32 v4, v0
	v_mov_b32_e32 v5, v0
	v_mov_b32_e32 v6, v0
	v_mov_b32_e32 v7, v0
	v_mov_b32_e32 v16, v0
	v_mov_b32_e32 v17, v0
	v_mov_b32_e32 v18, v0
	v_mov_b32_e32 v19, v0
	v_mov_b32_e32 v20, v0
	v_mov_b32_e32 v21, v0
	v_mov_b32_e32 v22, v0
	v_mov_b32_e32 v23, v0
	v_mov_b32_e32 v32, v0
	v_mov_b32_e32 v33, v0
	v_mov_b32_e32 v34, v0
	v_mov_b32_e32 v35, v0
	v_mov_b32_e32 v36, v0
	v_mov_b32_e32 v37, v0
	v_mov_b32_e32 v38, v0
	v_mov_b32_e32 v39, v0
	v_mov_b32_e32 v48, v0
	v_mov_b32_e32 v49, v0
	v_mov_b32_e32 v50, v0
	v_mov_b32_e32 v51, v0
	v_mov_b32_e32 v52, v0
	v_mov_b32_e32 v53, v0
	v_mov_b32_e32 v54, v0
	v_mov_b32_e32 v55, v0
	v_mov_b32_e32 v8, v0
	v_mov_b32_e32 v9, v0
	v_mov_b32_e32 v10, v0
	v_mov_b32_e32 v11, v0
	v_mov_b32_e32 v12, v0
	v_mov_b32_e32 v13, v0
	v_mov_b32_e32 v14, v0
	v_mov_b32_e32 v15, v0
	v_mov_b32_e32 v24, v0
	v_mov_b32_e32 v25, v0
	v_mov_b32_e32 v26, v0
	v_mov_b32_e32 v27, v0
	v_mov_b32_e32 v28, v0
	v_mov_b32_e32 v29, v0
	v_mov_b32_e32 v30, v0
	v_mov_b32_e32 v31, v0
	v_mov_b32_e32 v40, v0
	v_mov_b32_e32 v41, v0
	v_mov_b32_e32 v42, v0
	v_mov_b32_e32 v43, v0
	v_mov_b32_e32 v44, v0
	v_mov_b32_e32 v45, v0
	v_mov_b32_e32 v46, v0
	v_mov_b32_e32 v47, v0
	v_mov_b32_e32 v72, v0
	v_mov_b32_e32 v73, v0
	v_mov_b32_e32 v74, v0
	v_mov_b32_e32 v75, v0
	v_mov_b32_e32 v76, v0
	v_mov_b32_e32 v77, v0
	v_mov_b32_e32 v78, v0
	v_mov_b32_e32 v79, v0
	v_mov_b32_e32 v80, v0
	v_mov_b32_e32 v81, v0
	v_mov_b32_e32 v82, v0
	v_mov_b32_e32 v83, v0
	v_mov_b32_e32 v84, v0
	v_mov_b32_e32 v85, v0
	v_mov_b32_e32 v86, v0
	v_mov_b32_e32 v87, v0
	v_mov_b32_e32 v96, v0
	v_mov_b32_e32 v97, v0
	v_mov_b32_e32 v98, v0
	v_mov_b32_e32 v99, v0
	v_mov_b32_e32 v100, v0
	v_mov_b32_e32 v101, v0
	v_mov_b32_e32 v102, v0
	v_mov_b32_e32 v103, v0
	v_mov_b32_e32 v112, v0
	v_mov_b32_e32 v113, v0
	v_mov_b32_e32 v114, v0
	v_mov_b32_e32 v115, v0
	v_mov_b32_e32 v116, v0
	v_mov_b32_e32 v117, v0
	v_mov_b32_e32 v118, v0
	v_mov_b32_e32 v119, v0
	v_mov_b32_e32 v128, v0
	v_mov_b32_e32 v129, v0
	v_mov_b32_e32 v130, v0
	v_mov_b32_e32 v131, v0
	v_mov_b32_e32 v132, v0
	v_mov_b32_e32 v133, v0
	v_mov_b32_e32 v134, v0
	v_mov_b32_e32 v135, v0
	v_mov_b32_e32 v88, v0
	v_mov_b32_e32 v89, v0
	v_mov_b32_e32 v90, v0
	v_mov_b32_e32 v91, v0
	v_mov_b32_e32 v92, v0
	v_mov_b32_e32 v93, v0
	v_mov_b32_e32 v94, v0
	v_mov_b32_e32 v95, v0
	v_mov_b32_e32 v104, v0
	v_mov_b32_e32 v105, v0
	v_mov_b32_e32 v106, v0
	v_mov_b32_e32 v107, v0
	v_mov_b32_e32 v108, v0
	v_mov_b32_e32 v109, v0
	v_mov_b32_e32 v110, v0
	v_mov_b32_e32 v111, v0
	v_mov_b32_e32 v120, v0
	v_mov_b32_e32 v121, v0
	v_mov_b32_e32 v122, v0
	v_mov_b32_e32 v123, v0
	v_mov_b32_e32 v124, v0
	v_mov_b32_e32 v125, v0
	v_mov_b32_e32 v126, v0
	v_mov_b32_e32 v127, v0
	v_mov_b32_e32 v56, v0
	v_mov_b32_e32 v57, v0
	v_mov_b32_e32 v58, v0
	v_mov_b32_e32 v59, v0
	v_mov_b32_e32 v60, v0
	v_mov_b32_e32 v61, v0
	v_mov_b32_e32 v62, v0
	v_mov_b32_e32 v63, v0
	s_branch .LBB0_489

; #define PG8_STAGE(bufoff, gbase, voff) do { _Pragma("unroll") for (int _i = 0; _i < 2; ++_i) \
;         __builtin_amdgcn_global_load_lds((const unsigned*)((const char*)(gbase) + (voff)[_i]), (PG8_LAS unsigned*)(lds + (bufoff) + ldsw + _i * 8192), 16, 0, 0); } while (0)
; #define PG8_BAR __builtin_amdgcn_s_barrier()
; template <class Epi, class Sched>
; __device__ __forceinline__ void gemm_phase(PG8_LAS unsigned char* lds, const Gemm g, const Sched& S, const Epi& E, int wave_) {
;     ...
;         PG8_STAGE(PG8_SA(1, 1), nA + kstepA + hsA, voffA);
;         if (wr == 0) PG8_BAR;
;         E(acc, cur, wr, wc, fr, fq);
.LBB0_500:
	s_add_u32 s54, s88, 0x102000
	s_addc_u32 s55, s87, 0
	s_mov_b32 m0, s82
	v_lshl_add_u64 v[64:65], s[54:55], 0, v[198:199]
	global_load_lds_dwordx4 v[64:65], off
	v_lshl_add_u64 v[64:65], s[54:55], 0, v[194:195]
	s_mov_b32 m0, s83
	s_and_b64 vcc, exec, s[18:19]
	global_load_lds_dwordx4 v[64:65], off
	s_cbranch_vccz .LBB0_502
	s_barrier

; #define LAS __attribute__((address_space(3)))
; __global__ void __launch_bounds__(NWAVES * 64, 2) trunk_fwd(Args a) {
;     extern __shared__ __attribute__((aligned(16))) unsigned char lds_raw[];
;     Ctx F; F.lds = (LAS unsigned char*)lds_raw; F.tid = threadIdx.x; F.lane = F.tid & 63; F.wave = __builtin_amdgcn_readfirstlane(F.tid >> 6);
;     F.G = gridDim.x; F.wg = blockIdx.x;
	.amdhsa_kernel _Z9trunk_fwd4Args
		.amdhsa_group_segment_fixed_size 0
		.amdhsa_private_segment_fixed_size 0
		.amdhsa_kernarg_size 456
		.amdhsa_user_sgpr_count 2
		.amdhsa_user_sgpr_dispatch_ptr 0
		.amdhsa_user_sgpr_queue_ptr 0
		.amdhsa_user_sgpr_kernarg_segment_ptr 1
		.amdhsa_user_sgpr_dispatch_id 0
		.amdhsa_user_sgpr_kernarg_preload_length 0
		.amdhsa_user_sgpr_kernarg_preload_offset 0
		.amdhsa_user_sgpr_private_segment_size 0
		.amdhsa_uses_dynamic_stack 0
		.amdhsa_enable_private_segment 0
		.amdhsa_system_sgpr_workgroup_id_x 1
		.amdhsa_system_sgpr_workgroup_id_y 0
		.amdhsa_system_sgpr_workgroup_id_z 0
		.amdhsa_system_sgpr_workgroup_info 0
		.amdhsa_system_vgpr_workitem_id 0
		.amdhsa_next_free_vgpr 253
		.amdhsa_next_free_sgpr 100
		.amdhsa_accum_offset 256
		.amdhsa_reserve_vcc 1
		.amdhsa_float_round_mode_32 0
		.amdhsa_float_round_mode_16_64 0
		.amdhsa_float_denorm_mode_32 3
		.amdhsa_float_denorm_mode_16_64 3
		.amdhsa_dx10_clamp 1
		.amdhsa_ieee_mode 1
		.amdhsa_fp16_overflow 0
		.amdhsa_tg_split 0
		.amdhsa_exception_fp_ieee_invalid_op 0
		.amdhsa_exception_fp_denorm_src 0
		.amdhsa_exception_fp_ieee_div_zero 0
		.amdhsa_exception_fp_ieee_overflow 0
		.amdhsa_exception_fp_ieee_underflow 0
		.amdhsa_exception_fp_ieee_inexact 0
		.amdhsa_exception_int_div_zero 0
	.end_amdhsa_kernel

; #define LAS __attribute__((address_space(3)))
; __global__ void __launch_bounds__(NWAVES * 64, 2) trunk_fwd(Args a) {
;     extern __shared__ __attribute__((aligned(16))) unsigned char lds_raw[];
;     Ctx F; F.lds = (LAS unsigned char*)lds_raw; F.tid = threadIdx.x; F.lane = F.tid & 63; F.wave = __builtin_amdgcn_readfirstlane(F.tid >> 6);
;     F.G = gridDim.x; F.wg = blockIdx.x;
amdhsa.kernels:
  - .agpr_count:     0
    .args:
      - .offset:         0
        .size:           200
        .value_kind:     by_value
      - .offset:         200
        .size:           4
        .value_kind:     hidden_block_count_x
      - .offset:         204
        .size:           4
        .value_kind:     hidden_block_count_y
      - .offset:         208
        .size:           4
        .value_kind:     hidden_block_count_z
      - .offset:         212
        .size:           2
        .value_kind:     hidden_group_size_x
      - .offset:         214
        .size:           2
        .value_kind:     hidden_group_size_y
      - .offset:         216
        .size:           2
        .value_kind:     hidden_group_size_z
      - .offset:         218
        .size:           2
        .value_kind:     hidden_remainder_x
      - .offset:         220
        .size:           2
        .value_kind:     hidden_remainder_y
      - .offset:         222
        .size:           2
        .value_kind:     hidden_remainder_z
      - .offset:         240
        .size:           8
        .value_kind:     hidden_global_offset_x
      - .offset:         248
        .size:           8
        .value_kind:     hidden_global_offset_y
      - .offset:         256
        .size:           8
        .value_kind:     hidden_global_offset_z
      - .offset:         264
        .size:           2
        .value_kind:     hidden_grid_dims
      - .offset:         320
        .size:           4
        .value_kind:     hidden_dynamic_lds_size
    .group_segment_fixed_size: 0
    .kernarg_segment_align: 8
    .kernarg_segment_size: 456
    .language:       OpenCL C
    .language_version:
      - 2
      - 0
    .max_flat_workgroup_size: 512
    .name:           _Z9trunk_fwd4Args
    .private_segment_fixed_size: 0
    .sgpr_count:     106
    .sgpr_spill_count: 18
    .symbol:         _Z9trunk_fwd4Args.kd
    .uniform_work_group_size: 1
    .uses_dynamic_stack: false
    .vgpr_count:     253
    .vgpr_spill_count: 0
    .wavefront_size: 64
